# cross-unit prefetch extended to phase 15 (layer-1 moe gate/up) in addition to phase 7
# speedup vs baseline: 1.0750x; 1.0001x over previous
.LBB0_1433:
	s_cmpk_gt_i32 s47, 0x7ff
	s_cbranch_scc1 .LBB0_1437
	v_writelane_b32 v196, s96, 24
	v_writelane_b32 v197, s0, 18
	s_lshl_b32 s38, s47, 7
	v_writelane_b32 v196, s97, 25
	v_writelane_b32 v197, s1, 19
	v_readlane_b32 s8, v196, 6
	v_readlane_b32 s12, v196, 10
	v_readlane_b32 s13, v196, 11
	v_readlane_b32 s14, v196, 12
	v_readlane_b32 s15, v196, 13
	v_readlane_b32 s16, v196, 14
	v_readlane_b32 s17, v196, 15
	v_readlane_b32 s18, v196, 16
	v_readlane_b32 s19, v196, 17
	v_readlane_b32 s20, v196, 18
	v_readlane_b32 s21, v196, 19
	v_readlane_b32 s72, v197, 34
	s_lshl_b32 s39, s46, 7
	s_mov_b32 s3, 0
	v_mov_b32_e32 v67, 0
	s_mov_b64 s[0:1], 0x100
	s_add_i32 s56, 0, 0xc000
	s_mov_b64 s[40:41], 0x180
	s_mov_b64 s[42:43], 0x200
	s_mov_b32 s57, s47
	s_mov_b64 s[46:47], 0x280
	s_mov_b64 s[48:49], 0x300
	s_mov_b64 s[96:97], 0x380
	s_mov_b64 s[6:7], 0x400
	s_mov_b64 s[24:25], 0x500
	s_mov_b64 s[26:27], 0x580
	s_mov_b64 s[28:29], 0x600
	s_mov_b64 s[30:31], 0x680
	s_mov_b64 s[34:35], 0x700
	s_mov_b64 s[36:37], 0x780
	v_readlane_b32 s9, v196, 7
	v_readlane_b32 s22, v196, 20
	v_readlane_b32 s23, v196, 21
	s_mov_b64 s[20:21], 0x4040780
	s_mov_b64 s[18:19], 0x4020780
	s_mov_b64 s[16:17], 0x4000780
	s_mov_b64 s[14:15], 0x480
	s_mov_b64 s[12:13], 0x80
	v_readlane_b32 s82, v197, 44
	v_readlane_b32 s83, v197, 45
	v_readlane_b32 s10, v196, 8
	v_readlane_b32 s11, v196, 9
	v_readlane_b32 s73, v197, 35
	v_readlane_b32 s74, v197, 36
	v_readlane_b32 s75, v197, 37
	v_readlane_b32 s76, v197, 38
	v_readlane_b32 s77, v197, 39
	v_readlane_b32 s78, v197, 40
	v_readlane_b32 s79, v197, 41
	v_readlane_b32 s80, v197, 42
	v_readlane_b32 s81, v197, 43
	v_readlane_b32 s84, v197, 46
	v_readlane_b32 s85, v197, 47
	v_readlane_b32 s86, v197, 48
	v_readlane_b32 s87, v197, 49
	s_mov_b32 s98, s57
	s_mov_b32 s99, 0

.Lremap_done_15:
	s_lshl_b32 s38, s57, 7
	s_bfe_u32 s2, s57, 0x20002
	s_ashr_i32 s4, s57, 7
	s_lshl_b32 s5, s2, 4
	s_add_i32 s58, s5, s4
	v_mov_b32_e32 v1, v0
	s_lshl_b32 s5, s58, 9
	s_and_b32 s59, s38, 0x180
	s_waitcnt vmcnt(0) lgkmcnt(0)
	s_barrier
	s_or_b32 s5, s5, s59
	v_ashrrev_i32_e32 v2, 3, v1
	v_add_u32_e32 v4, s5, v2
	v_ashrrev_i32_e32 v5, 31, v4
	v_lshl_add_u64 v[4:5], v[4:5], 2, s[52:53]
	s_cmp_eq_u32 s99, 1
	s_cbranch_scc1 .Lpf15_have_idx
	global_load_dword v6, v[4:5], off
	global_load_dword v8, v[4:5], off offset:256
	s_branch .Lpf15_idx_join

.Lpf15_idx_join:
	s_ashr_i32 s5, s4, 31
	s_bfe_u32 s60, s57, 0x30004
	s_lshl_b64 s[4:5], s[4:5], 22
	s_add_u32 s4, s82, s4
	s_addc_u32 s5, s83, s5
	s_lshl_b32 s33, s60, 19
	s_add_u32 s4, s4, s33
	v_lshrrev_b32_e32 v3, 4, v1
	s_addc_u32 s5, s5, 0
	s_lshl_b32 s2, s2, 12
	v_mov_b32_e32 v16, v0
	v_xor_b32_e32 v3, v3, v1
	v_lshlrev_b32_e32 v3, 4, v3
	v_and_b32_e32 v66, 0x70, v3
	v_ashrrev_i32_e32 v3, 31, v2
	v_lshlrev_b64 v[2:3], 11, v[2:3]
	v_lshl_add_u64 v[2:3], s[4:5], 0, v[2:3]
	v_lshl_add_u64 v[2:3], v[2:3], 0, v[66:67]
	s_mov_b64 s[4:5], 0x4000000
	s_mov_b64 s[68:69], 0x4020080
	v_lshrrev_b32_e32 v17, 4, v16
	v_bfe_u32 v18, v16, 4, 2
	v_and_b32_e32 v19, 15, v16
	s_mov_b64 s[72:73], 0x4000100
	s_mov_b64 s[74:75], 0x4040100
	s_waitcnt vmcnt(1)
	v_ashrrev_i32_e32 v7, 31, v6
	s_waitcnt vmcnt(0)
	v_ashrrev_i32_e32 v9, 31, v8
	v_lshl_add_u64 v[4:5], v[6:7], 0, s[2:3]
	v_lshl_add_u64 v[6:7], v[8:9], 0, s[2:3]
	v_readfirstlane_b32 s2, v16
	s_lshl_b32 s2, s2, 4
	v_lshlrev_b64 v[4:5], 11, v[4:5]
	s_and_b32 s2, s2, 0xfffffc00
	v_lshl_add_u64 v[4:5], s[8:9], 0, v[4:5]
	v_lshlrev_b64 v[6:7], 11, v[6:7]
	s_add_i32 s64, s2, 0
	v_lshl_add_u64 v[4:5], v[4:5], 0, v[66:67]
	v_lshl_add_u64 v[6:7], s[8:9], 0, v[6:7]
	s_mov_b32 m0, s64
	s_add_i32 s2, s64, 0x2000
	v_lshl_add_u64 v[6:7], v[6:7], 0, v[66:67]
	s_cmp_eq_u32 s99, 1
	s_cbranch_scc1 .Lpf15_skip_glds
	global_load_lds_dwordx4 v[4:5], off
	s_mov_b32 m0, s2
	s_add_i32 s33, s64, 0x4000
	v_lshl_add_u64 v[8:9], v[2:3], 0, s[4:5]
	s_mov_b64 s[4:5], 0x4020000
	global_load_lds_dwordx4 v[6:7], off
	s_mov_b32 m0, s33
	s_add_i32 s61, s64, 0x6000
	v_lshl_add_u64 v[10:11], v[2:3], 0, s[4:5]
	s_mov_b64 s[4:5], 0x4040000
	global_load_lds_dwordx4 v[8:9], off
	s_mov_b32 m0, s61
	s_add_i32 s62, s64, 0x8000
	v_lshl_add_u64 v[12:13], v[2:3], 0, s[4:5]
	s_mov_b64 s[4:5], 0x4060000
	global_load_lds_dwordx4 v[10:11], off
	s_mov_b32 m0, s62
	s_add_i32 s63, s64, 0xa000
	v_lshl_add_u64 v[14:15], v[2:3], 0, s[4:5]
	global_load_lds_dwordx4 v[12:13], off
	s_mov_b32 m0, s63
	s_add_i32 s66, s64, 0xc000
	global_load_lds_dwordx4 v[14:15], off
	v_lshl_add_u64 v[8:9], v[4:5], 0, s[12:13]
	s_mov_b32 m0, s66
	s_add_i32 s65, s64, 0xe000
	global_load_lds_dwordx4 v[8:9], off
	v_lshl_add_u64 v[8:9], v[6:7], 0, s[12:13]
	s_mov_b32 m0, s65
	s_mov_b64 s[4:5], 0x4000080
	global_load_lds_dwordx4 v[8:9], off
	v_lshl_add_u64 v[8:9], v[2:3], 0, s[4:5]
	s_add_i32 s4, s64, 0x10000
	s_mov_b32 m0, s4
	s_add_i32 s5, s64, 0x12000
	global_load_lds_dwordx4 v[8:9], off
	v_lshl_add_u64 v[8:9], v[2:3], 0, s[68:69]
	s_mov_b32 m0, s5
	s_mov_b64 s[68:69], 0x4040080
	s_add_i32 s67, s64, 0x14000
	global_load_lds_dwordx4 v[8:9], off
	v_lshl_add_u64 v[8:9], v[2:3], 0, s[68:69]
	s_mov_b32 m0, s67
	s_mov_b64 s[68:69], 0x4060080
	global_load_lds_dwordx4 v[8:9], off
	v_lshl_add_u64 v[8:9], v[2:3], 0, s[68:69]
	s_add_i32 s68, s64, 0x16000
	s_mov_b32 m0, s68
	s_mov_b32 s69, 0x1ffffc0
	global_load_lds_dwordx4 v[8:9], off
	s_branch .Lpf15_glds_join
.Lpf15_skip_glds:
	s_add_i32 s33, s64, 0x4000
	s_mov_b64 s[4:5], 0x4020000
	s_add_i32 s61, s64, 0x6000
	s_mov_b64 s[4:5], 0x4040000
	s_add_i32 s62, s64, 0x8000
	s_mov_b64 s[4:5], 0x4060000
	s_add_i32 s63, s64, 0xa000
	s_add_i32 s66, s64, 0xc000
	s_add_i32 s65, s64, 0xe000
	s_mov_b64 s[4:5], 0x4000080
	s_add_i32 s4, s64, 0x10000
	s_add_i32 s5, s64, 0x12000
	s_mov_b64 s[68:69], 0x4040080
	s_add_i32 s67, s64, 0x14000
	s_mov_b64 s[68:69], 0x4060080
	s_add_i32 s68, s64, 0x16000
	s_mov_b32 s69, 0x1ffffc0
.Lpf15_glds_join:
	v_bfe_u32 v8, v16, 1, 3
	v_lshrrev_b32_e32 v9, 2, v16
	v_and_or_b32 v9, v9, s69, v19
	v_lshlrev_b32_e32 v10, 7, v16
	v_bitop3_b32 v11, v17, v8, 3 bitop3:0x6c
	v_bitop3_b32 v8, v18, v8, 4 bitop3:0x36
	v_lshlrev_b32_e32 v9, 7, v9
	v_and_b32_e32 v60, 0x6780, v10
	v_lshlrev_b32_e32 v11, 4, v11
	v_lshlrev_b32_e32 v61, 4, v8
	v_add_u32_e32 v10, 0x4000, v60
	v_or_b32_e32 v64, v11, v9
	v_or_b32_e32 v66, v61, v9
	v_or_b32_e32 v9, v11, v60
	s_add_i32 s69, s64, 0x18000
	s_waitcnt vmcnt(6)
	s_barrier
	v_or_b32_e32 v65, v11, v10
	v_or_b32_e32 v152, v61, v10
	v_add_u32_e32 v8, 0, v64
	v_add_u32_e32 v9, 0, v9
	v_lshl_add_u64 v[10:11], v[4:5], 0, s[0:1]
	s_mov_b32 m0, s69
	s_add_i32 s70, s64, 0x1a000
	ds_read_b128 v[12:15], v8
	ds_read_b128 v[16:19], v8 offset:2048
	ds_read_b128 v[20:23], v8 offset:4096
	ds_read_b128 v[24:27], v8 offset:6144
	ds_read_b128 v[28:31], v9 offset:22528
	ds_read_b128 v[32:35], v9 offset:20480
	ds_read_b128 v[36:39], v9 offset:18432
	ds_read_b128 v[40:43], v9 offset:16384
	global_load_lds_dwordx4 v[10:11], off
	v_lshl_add_u64 v[10:11], v[6:7], 0, s[0:1]
	s_mov_b32 m0, s70
	s_add_i32 s71, s64, 0x1c000
	global_load_lds_dwordx4 v[10:11], off
	v_lshl_add_u64 v[10:11], v[2:3], 0, s[72:73]
	s_mov_b32 m0, s71
	s_mov_b64 s[72:73], 0x4020100
	global_load_lds_dwordx4 v[10:11], off
	v_lshl_add_u64 v[10:11], v[2:3], 0, s[72:73]
	s_add_i32 s72, s64, 0x1e000
	s_mov_b32 m0, s72
	s_add_i32 s73, s64, 0x20000
	global_load_lds_dwordx4 v[10:11], off
	v_lshl_add_u64 v[10:11], v[2:3], 0, s[74:75]
	s_mov_b32 m0, s73
	s_mov_b64 s[74:75], 0x4060100
	global_load_lds_dwordx4 v[10:11], off
	v_lshl_add_u64 v[10:11], v[2:3], 0, s[74:75]
	s_add_i32 s74, s64, 0x22000
	s_mov_b32 m0, s74
	s_nop 0
	global_load_lds_dwordx4 v[10:11], off
	v_or_b32_e32 v11, v61, v60
	v_add_u32_e32 v10, 0, v66
	v_add_u32_e32 v11, 0, v11
	ds_read_b128 v[44:47], v10
	ds_read_b128 v[48:51], v10 offset:2048
	ds_read_b128 v[52:55], v10 offset:4096
	ds_read_b128 v[56:59], v10 offset:6144
	ds_read_b128 v[60:63], v11 offset:16384
	ds_read_b128 v[68:71], v11 offset:18432
	ds_read_b128 v[72:75], v11 offset:20480
	ds_read_b128 v[76:79], v11 offset:22528
	s_waitcnt lgkmcnt(8)
	v_mfma_f32_16x16x32_bf16 v[80:83], v[40:43], v[12:15], 0
	v_mfma_f32_16x16x32_bf16 v[84:87], v[36:39], v[12:15], 0
	v_mfma_f32_16x16x32_bf16 v[88:91], v[32:35], v[12:15], 0
	v_mfma_f32_16x16x32_bf16 v[92:95], v[28:31], v[12:15], 0
	v_mfma_f32_16x16x32_bf16 v[96:99], v[40:43], v[16:19], 0
	v_mfma_f32_16x16x32_bf16 v[100:103], v[36:39], v[16:19], 0
	v_mfma_f32_16x16x32_bf16 v[104:107], v[32:35], v[16:19], 0
	v_mfma_f32_16x16x32_bf16 v[14:17], v[28:31], v[16:19], 0
	v_mfma_f32_16x16x32_bf16 v[108:111], v[40:43], v[20:23], 0
	v_mfma_f32_16x16x32_bf16 v[112:115], v[36:39], v[20:23], 0
	v_mfma_f32_16x16x32_bf16 v[116:119], v[32:35], v[20:23], 0
	v_mfma_f32_16x16x32_bf16 v[18:21], v[28:31], v[20:23], 0
	v_mfma_f32_16x16x32_bf16 v[40:43], v[40:43], v[24:27], 0
	v_mfma_f32_16x16x32_bf16 v[36:39], v[36:39], v[24:27], 0
	v_mfma_f32_16x16x32_bf16 v[32:35], v[32:35], v[24:27], 0
	v_mfma_f32_16x16x32_bf16 v[22:25], v[28:31], v[24:27], 0
	s_waitcnt vmcnt(6) lgkmcnt(0)
	s_barrier
	v_add_u32_e32 v12, s56, v65
	ds_read_b128 v[26:29], v8 offset:49152
	ds_read_b128 v[120:123], v8 offset:51200
	ds_read_b128 v[124:127], v8 offset:53248
	ds_read_b128 v[128:131], v8 offset:55296
	ds_read_b128 v[132:135], v12
	ds_read_b128 v[136:139], v12 offset:2048
	ds_read_b128 v[140:143], v12 offset:4096
	ds_read_b128 v[144:147], v12 offset:6144
	v_mfma_f32_16x16x32_bf16 v[80:83], v[60:63], v[44:47], v[80:83]
	v_mfma_f32_16x16x32_bf16 v[84:87], v[68:71], v[44:47], v[84:87]
	v_mfma_f32_16x16x32_bf16 v[88:91], v[72:75], v[44:47], v[88:91]
	v_mfma_f32_16x16x32_bf16 v[44:47], v[76:79], v[44:47], v[92:95]
	v_mfma_f32_16x16x32_bf16 v[92:95], v[60:63], v[48:51], v[96:99]
	v_mfma_f32_16x16x32_bf16 v[96:99], v[68:71], v[48:51], v[100:103]
	v_mfma_f32_16x16x32_bf16 v[100:103], v[72:75], v[48:51], v[104:107]
	v_mfma_f32_16x16x32_bf16 v[14:17], v[76:79], v[48:51], v[14:17]
	v_mfma_f32_16x16x32_bf16 v[48:51], v[60:63], v[52:55], v[108:111]
	v_mfma_f32_16x16x32_bf16 v[104:107], v[68:71], v[52:55], v[112:115]
	v_mfma_f32_16x16x32_bf16 v[108:111], v[72:75], v[52:55], v[116:119]
	v_mfma_f32_16x16x32_bf16 v[18:21], v[76:79], v[52:55], v[18:21]
	v_mfma_f32_16x16x32_bf16 v[40:43], v[60:63], v[56:59], v[40:43]
	v_mfma_f32_16x16x32_bf16 v[36:39], v[68:71], v[56:59], v[36:39]
	v_mfma_f32_16x16x32_bf16 v[30:33], v[72:75], v[56:59], v[32:35]
	v_mfma_f32_16x16x32_bf16 v[22:25], v[76:79], v[56:59], v[22:25]
	s_mov_b32 m0, s64
	s_nop 0
	v_lshl_add_u64 v[34:35], v[4:5], 0, s[40:41]
	global_load_lds_dwordx4 v[34:35], off
	v_lshl_add_u64 v[34:35], v[6:7], 0, s[40:41]
	s_mov_b32 m0, s2
	s_mov_b64 s[76:77], 0x4000180
	global_load_lds_dwordx4 v[34:35], off
	v_lshl_add_u64 v[34:35], v[2:3], 0, s[76:77]
	s_mov_b32 m0, s33
	s_mov_b64 s[76:77], 0x4020180
	global_load_lds_dwordx4 v[34:35], off
	v_lshl_add_u64 v[34:35], v[2:3], 0, s[76:77]
	s_mov_b32 m0, s61
	s_mov_b64 s[76:77], 0x4040180
	global_load_lds_dwordx4 v[34:35], off
	v_lshl_add_u64 v[34:35], v[2:3], 0, s[76:77]
	s_mov_b32 m0, s62
	s_mov_b64 s[76:77], 0x4060180
	global_load_lds_dwordx4 v[34:35], off
	v_lshl_add_u64 v[34:35], v[2:3], 0, s[76:77]
	s_mov_b32 m0, s63
	v_add_u32_e32 v13, s56, v152
	global_load_lds_dwordx4 v[34:35], off
	ds_read_b128 v[52:55], v10 offset:49152
	ds_read_b128 v[56:59], v10 offset:51200
	ds_read_b128 v[60:63], v10 offset:53248
	ds_read_b128 v[68:71], v10 offset:55296
	ds_read_b128 v[72:75], v13
	ds_read_b128 v[76:79], v13 offset:2048
	ds_read_b128 v[112:115], v13 offset:4096
	ds_read_b128 v[116:119], v13 offset:6144
	s_waitcnt lgkmcnt(8)
	v_mfma_f32_16x16x32_bf16 v[80:83], v[132:135], v[26:29], v[80:83]
	v_mfma_f32_16x16x32_bf16 v[84:87], v[136:139], v[26:29], v[84:87]
	v_mfma_f32_16x16x32_bf16 v[88:91], v[140:143], v[26:29], v[88:91]
	v_mfma_f32_16x16x32_bf16 v[26:29], v[144:147], v[26:29], v[44:47]
	v_mfma_f32_16x16x32_bf16 v[44:47], v[132:135], v[120:123], v[92:95]
	v_mfma_f32_16x16x32_bf16 v[92:95], v[136:139], v[120:123], v[96:99]
	v_mfma_f32_16x16x32_bf16 v[96:99], v[140:143], v[120:123], v[100:103]
	v_mfma_f32_16x16x32_bf16 v[100:103], v[144:147], v[120:123], v[14:17]
	v_mfma_f32_16x16x32_bf16 v[48:51], v[132:135], v[124:127], v[48:51]
	v_mfma_f32_16x16x32_bf16 v[104:107], v[136:139], v[124:127], v[104:107]
	v_mfma_f32_16x16x32_bf16 v[108:111], v[140:143], v[124:127], v[108:111]
	v_mfma_f32_16x16x32_bf16 v[16:19], v[144:147], v[124:127], v[18:21]
	v_mfma_f32_16x16x32_bf16 v[40:43], v[132:135], v[128:131], v[40:43]
	v_mfma_f32_16x16x32_bf16 v[34:37], v[136:139], v[128:131], v[36:39]
	v_mfma_f32_16x16x32_bf16 v[30:33], v[140:143], v[128:131], v[30:33]
	v_mfma_f32_16x16x32_bf16 v[20:23], v[144:147], v[128:131], v[22:25]
	s_add_i32 s75, 0, 0x18000
	s_waitcnt vmcnt(6) lgkmcnt(0)
	s_barrier
	v_add_u32_e32 v14, s75, v64
	v_add_u32_e32 v15, s75, v65
	ds_read_b128 v[120:123], v14
	ds_read_b128 v[124:127], v14 offset:2048
	ds_read_b128 v[128:131], v14 offset:4096
	ds_read_b128 v[132:135], v14 offset:6144
	ds_read_b128 v[136:139], v15
	ds_read_b128 v[140:143], v15 offset:2048
	ds_read_b128 v[144:147], v15 offset:4096
	ds_read_b128 v[148:151], v15 offset:6144
	v_mfma_f32_16x16x32_bf16 v[80:83], v[72:75], v[52:55], v[80:83]
	v_mfma_f32_16x16x32_bf16 v[84:87], v[76:79], v[52:55], v[84:87]
	v_mfma_f32_16x16x32_bf16 v[88:91], v[112:115], v[52:55], v[88:91]
	v_mfma_f32_16x16x32_bf16 v[24:27], v[116:119], v[52:55], v[26:29]
	v_mfma_f32_16x16x32_bf16 v[44:47], v[72:75], v[56:59], v[44:47]
	v_mfma_f32_16x16x32_bf16 v[52:55], v[76:79], v[56:59], v[92:95]
	v_mfma_f32_16x16x32_bf16 v[92:95], v[112:115], v[56:59], v[96:99]
	v_mfma_f32_16x16x32_bf16 v[56:59], v[116:119], v[56:59], v[100:103]
	v_mfma_f32_16x16x32_bf16 v[48:51], v[72:75], v[60:63], v[48:51]
	v_mfma_f32_16x16x32_bf16 v[96:99], v[76:79], v[60:63], v[104:107]
	v_mfma_f32_16x16x32_bf16 v[100:103], v[112:115], v[60:63], v[108:111]
	v_mfma_f32_16x16x32_bf16 v[60:63], v[116:119], v[60:63], v[16:19]
	v_mfma_f32_16x16x32_bf16 v[38:41], v[72:75], v[68:71], v[40:43]
	v_mfma_f32_16x16x32_bf16 v[34:37], v[76:79], v[68:71], v[34:37]
	v_mfma_f32_16x16x32_bf16 v[28:31], v[112:115], v[68:71], v[30:33]
	v_mfma_f32_16x16x32_bf16 v[18:21], v[116:119], v[68:71], v[20:23]
	s_mov_b32 m0, s66
	v_lshl_add_u64 v[16:17], v[4:5], 0, s[42:43]
	global_load_lds_dwordx4 v[16:17], off
	v_lshl_add_u64 v[16:17], v[6:7], 0, s[42:43]
	s_mov_b32 m0, s65
	s_mov_b64 s[76:77], 0x4000200
	global_load_lds_dwordx4 v[16:17], off
	v_lshl_add_u64 v[16:17], v[2:3], 0, s[76:77]
	s_mov_b32 m0, s4
	s_mov_b64 s[76:77], 0x4020200
	global_load_lds_dwordx4 v[16:17], off
	v_lshl_add_u64 v[16:17], v[2:3], 0, s[76:77]
	s_mov_b32 m0, s5
	s_mov_b64 s[76:77], 0x4040200
	global_load_lds_dwordx4 v[16:17], off
	v_lshl_add_u64 v[16:17], v[2:3], 0, s[76:77]
	s_mov_b32 m0, s67
	s_mov_b64 s[76:77], 0x4060200
	global_load_lds_dwordx4 v[16:17], off
	v_lshl_add_u64 v[16:17], v[2:3], 0, s[76:77]
	s_mov_b32 m0, s68
	s_nop 0
	global_load_lds_dwordx4 v[16:17], off
	v_add_u32_e32 v16, s75, v66
	v_add_u32_e32 v17, s75, v152
	ds_read_b128 v[68:71], v16
	ds_read_b128 v[72:75], v16 offset:2048
	ds_read_b128 v[76:79], v16 offset:4096
	ds_read_b128 v[104:107], v16 offset:6144
	ds_read_b128 v[108:111], v17
	ds_read_b128 v[112:115], v17 offset:2048
	ds_read_b128 v[116:119], v17 offset:4096
	ds_read_b128 v[152:155], v17 offset:6144
	s_waitcnt lgkmcnt(8)
	v_mfma_f32_16x16x32_bf16 v[80:83], v[136:139], v[120:123], v[80:83]
	v_mfma_f32_16x16x32_bf16 v[84:87], v[140:143], v[120:123], v[84:87]
	v_mfma_f32_16x16x32_bf16 v[88:91], v[144:147], v[120:123], v[88:91]
	v_mfma_f32_16x16x32_bf16 v[22:25], v[148:151], v[120:123], v[24:27]
	v_mfma_f32_16x16x32_bf16 v[42:45], v[136:139], v[124:127], v[44:47]
	v_mfma_f32_16x16x32_bf16 v[52:55], v[140:143], v[124:127], v[52:55]
	v_mfma_f32_16x16x32_bf16 v[92:95], v[144:147], v[124:127], v[92:95]
	v_mfma_f32_16x16x32_bf16 v[56:59], v[148:151], v[124:127], v[56:59]
	v_mfma_f32_16x16x32_bf16 v[46:49], v[136:139], v[128:131], v[48:51]
	v_mfma_f32_16x16x32_bf16 v[96:99], v[140:143], v[128:131], v[96:99]
	v_mfma_f32_16x16x32_bf16 v[100:103], v[144:147], v[128:131], v[100:103]
	v_mfma_f32_16x16x32_bf16 v[60:63], v[148:151], v[128:131], v[60:63]
	v_mfma_f32_16x16x32_bf16 v[38:41], v[136:139], v[132:135], v[38:41]
	v_mfma_f32_16x16x32_bf16 v[32:35], v[140:143], v[132:135], v[34:37]
	v_mfma_f32_16x16x32_bf16 v[26:29], v[144:147], v[132:135], v[28:31]
	v_mfma_f32_16x16x32_bf16 v[18:21], v[148:151], v[132:135], v[18:21]
	s_waitcnt vmcnt(6) lgkmcnt(0)
	s_barrier
	ds_read_b128 v[120:123], v8
	ds_read_b128 v[124:127], v8 offset:2048
	ds_read_b128 v[128:131], v8 offset:4096
	ds_read_b128 v[132:135], v8 offset:6144
	ds_read_b128 v[136:139], v9 offset:16384
	ds_read_b128 v[140:143], v9 offset:18432
	ds_read_b128 v[144:147], v9 offset:20480
	ds_read_b128 v[148:151], v9 offset:22528
	v_mfma_f32_16x16x32_bf16 v[80:83], v[108:111], v[68:71], v[80:83]
	v_mfma_f32_16x16x32_bf16 v[84:87], v[112:115], v[68:71], v[84:87]
	v_mfma_f32_16x16x32_bf16 v[88:91], v[116:119], v[68:71], v[88:91]
	v_mfma_f32_16x16x32_bf16 v[22:25], v[152:155], v[68:71], v[22:25]
	v_mfma_f32_16x16x32_bf16 v[42:45], v[108:111], v[72:75], v[42:45]
	v_mfma_f32_16x16x32_bf16 v[50:53], v[112:115], v[72:75], v[52:55]
	v_mfma_f32_16x16x32_bf16 v[68:71], v[116:119], v[72:75], v[92:95]
	v_mfma_f32_16x16x32_bf16 v[54:57], v[152:155], v[72:75], v[56:59]
	v_mfma_f32_16x16x32_bf16 v[46:49], v[108:111], v[76:79], v[46:49]
	v_mfma_f32_16x16x32_bf16 v[72:75], v[112:115], v[76:79], v[96:99]
	v_mfma_f32_16x16x32_bf16 v[92:95], v[116:119], v[76:79], v[100:103]
	v_mfma_f32_16x16x32_bf16 v[58:61], v[152:155], v[76:79], v[60:63]
	v_mfma_f32_16x16x32_bf16 v[36:39], v[108:111], v[104:107], v[38:41]
	v_mfma_f32_16x16x32_bf16 v[30:33], v[112:115], v[104:107], v[32:35]
	v_mfma_f32_16x16x32_bf16 v[26:29], v[116:119], v[104:107], v[26:29]
	v_mfma_f32_16x16x32_bf16 v[18:21], v[152:155], v[104:107], v[18:21]
	s_mov_b32 m0, s69
	v_lshl_add_u64 v[34:35], v[4:5], 0, s[46:47]
	global_load_lds_dwordx4 v[34:35], off
	v_lshl_add_u64 v[34:35], v[6:7], 0, s[46:47]
	s_mov_b32 m0, s70
	s_mov_b64 s[76:77], 0x4000280
	global_load_lds_dwordx4 v[34:35], off
	v_lshl_add_u64 v[34:35], v[2:3], 0, s[76:77]
	s_mov_b32 m0, s71
	s_mov_b64 s[76:77], 0x4020280
	global_load_lds_dwordx4 v[34:35], off
	v_lshl_add_u64 v[34:35], v[2:3], 0, s[76:77]
	s_mov_b32 m0, s72
	s_mov_b64 s[76:77], 0x4040280
	global_load_lds_dwordx4 v[34:35], off
	v_lshl_add_u64 v[34:35], v[2:3], 0, s[76:77]
	s_mov_b32 m0, s73
	s_mov_b64 s[76:77], 0x4060280
	global_load_lds_dwordx4 v[34:35], off
	v_lshl_add_u64 v[34:35], v[2:3], 0, s[76:77]
	s_mov_b32 m0, s74
	s_nop 0
	global_load_lds_dwordx4 v[34:35], off
	ds_read_b128 v[62:65], v10
	ds_read_b128 v[76:79], v10 offset:2048
	ds_read_b128 v[96:99], v10 offset:4096
	ds_read_b128 v[100:103], v10 offset:6144
	ds_read_b128 v[104:107], v11 offset:16384
	ds_read_b128 v[108:111], v11 offset:18432
	ds_read_b128 v[112:115], v11 offset:20480
	ds_read_b128 v[116:119], v11 offset:22528
	s_waitcnt lgkmcnt(8)
	v_mfma_f32_16x16x32_bf16 v[80:83], v[136:139], v[120:123], v[80:83]
	v_mfma_f32_16x16x32_bf16 v[84:87], v[140:143], v[120:123], v[84:87]
	v_mfma_f32_16x16x32_bf16 v[88:91], v[144:147], v[120:123], v[88:91]
	v_mfma_f32_16x16x32_bf16 v[22:25], v[148:151], v[120:123], v[22:25]
	v_mfma_f32_16x16x32_bf16 v[40:43], v[136:139], v[124:127], v[42:45]
	v_mfma_f32_16x16x32_bf16 v[50:53], v[140:143], v[124:127], v[50:53]
	v_mfma_f32_16x16x32_bf16 v[68:71], v[144:147], v[124:127], v[68:71]
	v_mfma_f32_16x16x32_bf16 v[54:57], v[148:151], v[124:127], v[54:57]
	v_mfma_f32_16x16x32_bf16 v[44:47], v[136:139], v[128:131], v[46:49]
	v_mfma_f32_16x16x32_bf16 v[72:75], v[140:143], v[128:131], v[72:75]
	v_mfma_f32_16x16x32_bf16 v[92:95], v[144:147], v[128:131], v[92:95]
	v_mfma_f32_16x16x32_bf16 v[58:61], v[148:151], v[128:131], v[58:61]
	v_mfma_f32_16x16x32_bf16 v[34:37], v[136:139], v[132:135], v[36:39]
	v_mfma_f32_16x16x32_bf16 v[30:33], v[140:143], v[132:135], v[30:33]
	v_mfma_f32_16x16x32_bf16 v[26:29], v[144:147], v[132:135], v[26:29]
	v_mfma_f32_16x16x32_bf16 v[18:21], v[148:151], v[132:135], v[18:21]
	s_waitcnt vmcnt(6) lgkmcnt(0)
	s_barrier
	ds_read_b128 v[120:123], v8 offset:49152
	ds_read_b128 v[124:127], v8 offset:51200
	ds_read_b128 v[128:131], v8 offset:53248
	ds_read_b128 v[132:135], v8 offset:55296
	ds_read_b128 v[136:139], v12
	ds_read_b128 v[140:143], v12 offset:2048
	ds_read_b128 v[144:147], v12 offset:4096
	ds_read_b128 v[148:151], v12 offset:6144
	v_mfma_f32_16x16x32_bf16 v[80:83], v[104:107], v[62:65], v[80:83]
	v_mfma_f32_16x16x32_bf16 v[84:87], v[108:111], v[62:65], v[84:87]
	v_mfma_f32_16x16x32_bf16 v[88:91], v[112:115], v[62:65], v[88:91]
	v_mfma_f32_16x16x32_bf16 v[22:25], v[116:119], v[62:65], v[22:25]
	v_mfma_f32_16x16x32_bf16 v[38:41], v[104:107], v[76:79], v[40:43]
	v_mfma_f32_16x16x32_bf16 v[48:51], v[108:111], v[76:79], v[50:53]
	v_mfma_f32_16x16x32_bf16 v[62:65], v[112:115], v[76:79], v[68:71]
	v_mfma_f32_16x16x32_bf16 v[52:55], v[116:119], v[76:79], v[54:57]
	v_mfma_f32_16x16x32_bf16 v[42:45], v[104:107], v[96:99], v[44:47]
	v_mfma_f32_16x16x32_bf16 v[68:71], v[108:111], v[96:99], v[72:75]
	v_mfma_f32_16x16x32_bf16 v[72:75], v[112:115], v[96:99], v[92:95]
	v_mfma_f32_16x16x32_bf16 v[56:59], v[116:119], v[96:99], v[58:61]
	v_mfma_f32_16x16x32_bf16 v[34:37], v[104:107], v[100:103], v[34:37]
	v_mfma_f32_16x16x32_bf16 v[30:33], v[108:111], v[100:103], v[30:33]
	v_mfma_f32_16x16x32_bf16 v[26:29], v[112:115], v[100:103], v[26:29]
	v_mfma_f32_16x16x32_bf16 v[18:21], v[116:119], v[100:103], v[18:21]
	s_mov_b32 m0, s64
	v_lshl_add_u64 v[46:47], v[4:5], 0, s[48:49]
	global_load_lds_dwordx4 v[46:47], off
	v_lshl_add_u64 v[46:47], v[6:7], 0, s[48:49]
	s_mov_b32 m0, s2
	s_mov_b64 s[76:77], 0x4000300
	global_load_lds_dwordx4 v[46:47], off
	v_lshl_add_u64 v[46:47], v[2:3], 0, s[76:77]
	s_mov_b32 m0, s33
	s_mov_b64 s[76:77], 0x4020300
	global_load_lds_dwordx4 v[46:47], off
	v_lshl_add_u64 v[46:47], v[2:3], 0, s[76:77]
	s_mov_b32 m0, s61
	s_mov_b64 s[76:77], 0x4040300
	global_load_lds_dwordx4 v[46:47], off
	v_lshl_add_u64 v[46:47], v[2:3], 0, s[76:77]
	s_mov_b32 m0, s62
	s_mov_b64 s[76:77], 0x4060300
	global_load_lds_dwordx4 v[46:47], off
	v_lshl_add_u64 v[46:47], v[2:3], 0, s[76:77]
	s_mov_b32 m0, s63
	s_nop 0
	global_load_lds_dwordx4 v[46:47], off
	ds_read_b128 v[76:79], v10 offset:49152
	ds_read_b128 v[92:95], v10 offset:51200
	ds_read_b128 v[96:99], v10 offset:53248
	ds_read_b128 v[100:103], v10 offset:55296
	ds_read_b128 v[104:107], v13
	ds_read_b128 v[108:111], v13 offset:2048
	ds_read_b128 v[112:115], v13 offset:4096
	ds_read_b128 v[116:119], v13 offset:6144
	s_waitcnt lgkmcnt(8)
	v_mfma_f32_16x16x32_bf16 v[80:83], v[136:139], v[120:123], v[80:83]
	v_mfma_f32_16x16x32_bf16 v[84:87], v[140:143], v[120:123], v[84:87]
	v_mfma_f32_16x16x32_bf16 v[88:91], v[144:147], v[120:123], v[88:91]
	v_mfma_f32_16x16x32_bf16 v[22:25], v[148:151], v[120:123], v[22:25]
	v_mfma_f32_16x16x32_bf16 v[38:41], v[136:139], v[124:127], v[38:41]
	v_mfma_f32_16x16x32_bf16 v[46:49], v[140:143], v[124:127], v[48:51]
	v_mfma_f32_16x16x32_bf16 v[60:63], v[144:147], v[124:127], v[62:65]
	v_mfma_f32_16x16x32_bf16 v[50:53], v[148:151], v[124:127], v[52:55]
	v_mfma_f32_16x16x32_bf16 v[42:45], v[136:139], v[128:131], v[42:45]
	v_mfma_f32_16x16x32_bf16 v[68:71], v[140:143], v[128:131], v[68:71]
	v_mfma_f32_16x16x32_bf16 v[72:75], v[144:147], v[128:131], v[72:75]
	v_mfma_f32_16x16x32_bf16 v[54:57], v[148:151], v[128:131], v[56:59]
	v_mfma_f32_16x16x32_bf16 v[34:37], v[136:139], v[132:135], v[34:37]
	v_mfma_f32_16x16x32_bf16 v[30:33], v[140:143], v[132:135], v[30:33]
	v_mfma_f32_16x16x32_bf16 v[26:29], v[144:147], v[132:135], v[26:29]
	v_mfma_f32_16x16x32_bf16 v[18:21], v[148:151], v[132:135], v[18:21]
	s_waitcnt vmcnt(6) lgkmcnt(0)
	s_barrier
	ds_read_b128 v[120:123], v14
	ds_read_b128 v[124:127], v14 offset:2048
	ds_read_b128 v[128:131], v14 offset:4096
	ds_read_b128 v[132:135], v14 offset:6144
	ds_read_b128 v[136:139], v15
	ds_read_b128 v[140:143], v15 offset:2048
	ds_read_b128 v[144:147], v15 offset:4096
	ds_read_b128 v[148:151], v15 offset:6144
	v_mfma_f32_16x16x32_bf16 v[80:83], v[104:107], v[76:79], v[80:83]
	v_mfma_f32_16x16x32_bf16 v[84:87], v[108:111], v[76:79], v[84:87]
	v_mfma_f32_16x16x32_bf16 v[88:91], v[112:115], v[76:79], v[88:91]
	v_mfma_f32_16x16x32_bf16 v[22:25], v[116:119], v[76:79], v[22:25]
	v_mfma_f32_16x16x32_bf16 v[38:41], v[104:107], v[92:95], v[38:41]
	v_mfma_f32_16x16x32_bf16 v[46:49], v[108:111], v[92:95], v[46:49]
	v_mfma_f32_16x16x32_bf16 v[58:61], v[112:115], v[92:95], v[60:63]
	v_mfma_f32_16x16x32_bf16 v[50:53], v[116:119], v[92:95], v[50:53]
	v_mfma_f32_16x16x32_bf16 v[42:45], v[104:107], v[96:99], v[42:45]
	v_mfma_f32_16x16x32_bf16 v[62:65], v[108:111], v[96:99], v[68:71]
	v_mfma_f32_16x16x32_bf16 v[68:71], v[112:115], v[96:99], v[72:75]
	v_mfma_f32_16x16x32_bf16 v[54:57], v[116:119], v[96:99], v[54:57]
	v_mfma_f32_16x16x32_bf16 v[34:37], v[104:107], v[100:103], v[34:37]
	v_mfma_f32_16x16x32_bf16 v[30:33], v[108:111], v[100:103], v[30:33]
	v_mfma_f32_16x16x32_bf16 v[26:29], v[112:115], v[100:103], v[26:29]
	v_mfma_f32_16x16x32_bf16 v[18:21], v[116:119], v[100:103], v[18:21]
	s_mov_b32 m0, s66
	v_lshl_add_u64 v[72:73], v[4:5], 0, s[96:97]
	global_load_lds_dwordx4 v[72:73], off
	v_lshl_add_u64 v[72:73], v[6:7], 0, s[96:97]
	s_mov_b32 m0, s65
	s_mov_b64 s[76:77], 0x4000380
	global_load_lds_dwordx4 v[72:73], off
	v_lshl_add_u64 v[72:73], v[2:3], 0, s[76:77]
	s_mov_b32 m0, s4
	s_mov_b64 s[76:77], 0x4020380
	global_load_lds_dwordx4 v[72:73], off
	v_lshl_add_u64 v[72:73], v[2:3], 0, s[76:77]
	s_mov_b32 m0, s5
	s_mov_b64 s[76:77], 0x4040380
	global_load_lds_dwordx4 v[72:73], off
	v_lshl_add_u64 v[72:73], v[2:3], 0, s[76:77]
	s_mov_b32 m0, s67
	s_mov_b64 s[76:77], 0x4060380
	global_load_lds_dwordx4 v[72:73], off
	v_lshl_add_u64 v[72:73], v[2:3], 0, s[76:77]
	s_mov_b32 m0, s68
	s_nop 0
	global_load_lds_dwordx4 v[72:73], off
	ds_read_b128 v[72:75], v16
	ds_read_b128 v[76:79], v16 offset:2048
	ds_read_b128 v[92:95], v16 offset:4096
	ds_read_b128 v[96:99], v16 offset:6144
	ds_read_b128 v[100:103], v17
	ds_read_b128 v[104:107], v17 offset:2048
	ds_read_b128 v[108:111], v17 offset:4096
	ds_read_b128 v[112:115], v17 offset:6144
	s_waitcnt lgkmcnt(8)
	v_mfma_f32_16x16x32_bf16 v[80:83], v[136:139], v[120:123], v[80:83]
	v_mfma_f32_16x16x32_bf16 v[84:87], v[140:143], v[120:123], v[84:87]
	v_mfma_f32_16x16x32_bf16 v[88:91], v[144:147], v[120:123], v[88:91]
	v_mfma_f32_16x16x32_bf16 v[22:25], v[148:151], v[120:123], v[22:25]
	v_mfma_f32_16x16x32_bf16 v[38:41], v[136:139], v[124:127], v[38:41]
	v_mfma_f32_16x16x32_bf16 v[46:49], v[140:143], v[124:127], v[46:49]
	v_mfma_f32_16x16x32_bf16 v[58:61], v[144:147], v[124:127], v[58:61]
	v_mfma_f32_16x16x32_bf16 v[50:53], v[148:151], v[124:127], v[50:53]
	v_mfma_f32_16x16x32_bf16 v[42:45], v[136:139], v[128:131], v[42:45]
	v_mfma_f32_16x16x32_bf16 v[62:65], v[140:143], v[128:131], v[62:65]
	v_mfma_f32_16x16x32_bf16 v[68:71], v[144:147], v[128:131], v[68:71]
	v_mfma_f32_16x16x32_bf16 v[54:57], v[148:151], v[128:131], v[54:57]
	v_mfma_f32_16x16x32_bf16 v[34:37], v[136:139], v[132:135], v[34:37]
	v_mfma_f32_16x16x32_bf16 v[30:33], v[140:143], v[132:135], v[30:33]
	v_mfma_f32_16x16x32_bf16 v[26:29], v[144:147], v[132:135], v[26:29]
	v_mfma_f32_16x16x32_bf16 v[18:21], v[148:151], v[132:135], v[18:21]
	s_waitcnt vmcnt(6) lgkmcnt(0)
	s_barrier
	ds_read_b128 v[116:119], v8
	ds_read_b128 v[120:123], v8 offset:2048
	ds_read_b128 v[124:127], v8 offset:4096
	ds_read_b128 v[128:131], v8 offset:6144
	ds_read_b128 v[132:135], v9 offset:16384
	ds_read_b128 v[136:139], v9 offset:18432
	ds_read_b128 v[140:143], v9 offset:20480
	ds_read_b128 v[144:147], v9 offset:22528
	v_mfma_f32_16x16x32_bf16 v[80:83], v[100:103], v[72:75], v[80:83]
	v_mfma_f32_16x16x32_bf16 v[84:87], v[104:107], v[72:75], v[84:87]
	v_mfma_f32_16x16x32_bf16 v[88:91], v[108:111], v[72:75], v[88:91]
	v_mfma_f32_16x16x32_bf16 v[22:25], v[112:115], v[72:75], v[22:25]
	v_mfma_f32_16x16x32_bf16 v[38:41], v[100:103], v[76:79], v[38:41]
	v_mfma_f32_16x16x32_bf16 v[46:49], v[104:107], v[76:79], v[46:49]
	v_mfma_f32_16x16x32_bf16 v[58:61], v[108:111], v[76:79], v[58:61]
	v_mfma_f32_16x16x32_bf16 v[50:53], v[112:115], v[76:79], v[50:53]
	v_mfma_f32_16x16x32_bf16 v[42:45], v[100:103], v[92:95], v[42:45]
	v_mfma_f32_16x16x32_bf16 v[62:65], v[104:107], v[92:95], v[62:65]
	v_mfma_f32_16x16x32_bf16 v[68:71], v[108:111], v[92:95], v[68:71]
	v_mfma_f32_16x16x32_bf16 v[54:57], v[112:115], v[92:95], v[54:57]
	v_mfma_f32_16x16x32_bf16 v[34:37], v[100:103], v[96:99], v[34:37]
	v_mfma_f32_16x16x32_bf16 v[30:33], v[104:107], v[96:99], v[30:33]
	v_mfma_f32_16x16x32_bf16 v[26:29], v[108:111], v[96:99], v[26:29]
	v_mfma_f32_16x16x32_bf16 v[18:21], v[112:115], v[96:99], v[18:21]
	s_mov_b32 m0, s69
	v_lshl_add_u64 v[72:73], v[4:5], 0, s[6:7]
	global_load_lds_dwordx4 v[72:73], off
	v_lshl_add_u64 v[72:73], v[6:7], 0, s[6:7]
	s_mov_b32 m0, s70
	s_mov_b64 s[76:77], 0x4000400
	global_load_lds_dwordx4 v[72:73], off
	v_lshl_add_u64 v[72:73], v[2:3], 0, s[76:77]
	s_mov_b32 m0, s71
	s_mov_b64 s[76:77], 0x4020400
	global_load_lds_dwordx4 v[72:73], off
	v_lshl_add_u64 v[72:73], v[2:3], 0, s[76:77]
	s_mov_b32 m0, s72
	s_mov_b64 s[76:77], 0x4040400
	global_load_lds_dwordx4 v[72:73], off
	v_lshl_add_u64 v[72:73], v[2:3], 0, s[76:77]
	s_mov_b32 m0, s73
	s_mov_b64 s[76:77], 0x4060400
	global_load_lds_dwordx4 v[72:73], off
	v_lshl_add_u64 v[72:73], v[2:3], 0, s[76:77]
	s_mov_b32 m0, s74
	s_nop 0
	global_load_lds_dwordx4 v[72:73], off
	ds_read_b128 v[72:75], v10
	ds_read_b128 v[76:79], v10 offset:2048
	ds_read_b128 v[92:95], v10 offset:4096
	ds_read_b128 v[96:99], v10 offset:6144
	ds_read_b128 v[100:103], v11 offset:16384
	ds_read_b128 v[104:107], v11 offset:18432
	ds_read_b128 v[108:111], v11 offset:20480
	ds_read_b128 v[112:115], v11 offset:22528
	s_waitcnt lgkmcnt(8)
	v_mfma_f32_16x16x32_bf16 v[80:83], v[132:135], v[116:119], v[80:83]
	v_mfma_f32_16x16x32_bf16 v[84:87], v[136:139], v[116:119], v[84:87]
	v_mfma_f32_16x16x32_bf16 v[88:91], v[140:143], v[116:119], v[88:91]
	v_mfma_f32_16x16x32_bf16 v[22:25], v[144:147], v[116:119], v[22:25]
	v_mfma_f32_16x16x32_bf16 v[38:41], v[132:135], v[120:123], v[38:41]
	v_mfma_f32_16x16x32_bf16 v[46:49], v[136:139], v[120:123], v[46:49]
	v_mfma_f32_16x16x32_bf16 v[58:61], v[140:143], v[120:123], v[58:61]
	v_mfma_f32_16x16x32_bf16 v[50:53], v[144:147], v[120:123], v[50:53]
	v_mfma_f32_16x16x32_bf16 v[42:45], v[132:135], v[124:127], v[42:45]
	v_mfma_f32_16x16x32_bf16 v[62:65], v[136:139], v[124:127], v[62:65]
	v_mfma_f32_16x16x32_bf16 v[68:71], v[140:143], v[124:127], v[68:71]
	v_mfma_f32_16x16x32_bf16 v[54:57], v[144:147], v[124:127], v[54:57]
	v_mfma_f32_16x16x32_bf16 v[34:37], v[132:135], v[128:131], v[34:37]
	v_mfma_f32_16x16x32_bf16 v[30:33], v[136:139], v[128:131], v[30:33]
	v_mfma_f32_16x16x32_bf16 v[26:29], v[140:143], v[128:131], v[26:29]
	v_mfma_f32_16x16x32_bf16 v[18:21], v[144:147], v[128:131], v[18:21]
	s_waitcnt vmcnt(6) lgkmcnt(0)
	s_barrier
	ds_read_b128 v[116:119], v8 offset:49152
	ds_read_b128 v[120:123], v8 offset:51200
	ds_read_b128 v[124:127], v8 offset:53248
	ds_read_b128 v[128:131], v8 offset:55296
	ds_read_b128 v[132:135], v12
	ds_read_b128 v[136:139], v12 offset:2048
	ds_read_b128 v[140:143], v12 offset:4096
	ds_read_b128 v[144:147], v12 offset:6144
	v_mfma_f32_16x16x32_bf16 v[80:83], v[100:103], v[72:75], v[80:83]
	v_mfma_f32_16x16x32_bf16 v[84:87], v[104:107], v[72:75], v[84:87]
	v_mfma_f32_16x16x32_bf16 v[88:91], v[108:111], v[72:75], v[88:91]
	v_mfma_f32_16x16x32_bf16 v[22:25], v[112:115], v[72:75], v[22:25]
	v_mfma_f32_16x16x32_bf16 v[38:41], v[100:103], v[76:79], v[38:41]
	v_mfma_f32_16x16x32_bf16 v[46:49], v[104:107], v[76:79], v[46:49]
	v_mfma_f32_16x16x32_bf16 v[58:61], v[108:111], v[76:79], v[58:61]
	v_mfma_f32_16x16x32_bf16 v[50:53], v[112:115], v[76:79], v[50:53]
	v_mfma_f32_16x16x32_bf16 v[42:45], v[100:103], v[92:95], v[42:45]
	v_mfma_f32_16x16x32_bf16 v[62:65], v[104:107], v[92:95], v[62:65]
	v_mfma_f32_16x16x32_bf16 v[68:71], v[108:111], v[92:95], v[68:71]
	v_mfma_f32_16x16x32_bf16 v[54:57], v[112:115], v[92:95], v[54:57]
	v_mfma_f32_16x16x32_bf16 v[34:37], v[100:103], v[96:99], v[34:37]
	v_mfma_f32_16x16x32_bf16 v[30:33], v[104:107], v[96:99], v[30:33]
	v_mfma_f32_16x16x32_bf16 v[26:29], v[108:111], v[96:99], v[26:29]
	v_mfma_f32_16x16x32_bf16 v[18:21], v[112:115], v[96:99], v[18:21]
	s_mov_b32 m0, s64
	v_lshl_add_u64 v[72:73], v[4:5], 0, s[14:15]
	global_load_lds_dwordx4 v[72:73], off
	v_lshl_add_u64 v[72:73], v[6:7], 0, s[14:15]
	s_mov_b32 m0, s2
	s_mov_b64 s[76:77], 0x4000480
	global_load_lds_dwordx4 v[72:73], off
	v_lshl_add_u64 v[72:73], v[2:3], 0, s[76:77]
	s_mov_b32 m0, s33
	s_mov_b64 s[76:77], 0x4020480
	global_load_lds_dwordx4 v[72:73], off
	v_lshl_add_u64 v[72:73], v[2:3], 0, s[76:77]
	s_mov_b32 m0, s61
	s_mov_b64 s[76:77], 0x4040480
	global_load_lds_dwordx4 v[72:73], off
	v_lshl_add_u64 v[72:73], v[2:3], 0, s[76:77]
	s_mov_b32 m0, s62
	s_mov_b64 s[76:77], 0x4060480
	global_load_lds_dwordx4 v[72:73], off
	v_lshl_add_u64 v[72:73], v[2:3], 0, s[76:77]
	s_mov_b32 m0, s63
	s_nop 0
	global_load_lds_dwordx4 v[72:73], off
	ds_read_b128 v[72:75], v10 offset:49152
	ds_read_b128 v[76:79], v10 offset:51200
	ds_read_b128 v[92:95], v10 offset:53248
	ds_read_b128 v[96:99], v10 offset:55296
	ds_read_b128 v[100:103], v13
	ds_read_b128 v[104:107], v13 offset:2048
	ds_read_b128 v[108:111], v13 offset:4096
	ds_read_b128 v[112:115], v13 offset:6144
	s_waitcnt lgkmcnt(8)
	v_mfma_f32_16x16x32_bf16 v[80:83], v[132:135], v[116:119], v[80:83]
	v_mfma_f32_16x16x32_bf16 v[84:87], v[136:139], v[116:119], v[84:87]
	v_mfma_f32_16x16x32_bf16 v[88:91], v[140:143], v[116:119], v[88:91]
	v_mfma_f32_16x16x32_bf16 v[22:25], v[144:147], v[116:119], v[22:25]
	v_mfma_f32_16x16x32_bf16 v[38:41], v[132:135], v[120:123], v[38:41]
	v_mfma_f32_16x16x32_bf16 v[46:49], v[136:139], v[120:123], v[46:49]
	v_mfma_f32_16x16x32_bf16 v[58:61], v[140:143], v[120:123], v[58:61]
	v_mfma_f32_16x16x32_bf16 v[50:53], v[144:147], v[120:123], v[50:53]
	v_mfma_f32_16x16x32_bf16 v[42:45], v[132:135], v[124:127], v[42:45]
	v_mfma_f32_16x16x32_bf16 v[62:65], v[136:139], v[124:127], v[62:65]
	v_mfma_f32_16x16x32_bf16 v[68:71], v[140:143], v[124:127], v[68:71]
	v_mfma_f32_16x16x32_bf16 v[54:57], v[144:147], v[124:127], v[54:57]
	v_mfma_f32_16x16x32_bf16 v[34:37], v[132:135], v[128:131], v[34:37]
	v_mfma_f32_16x16x32_bf16 v[30:33], v[136:139], v[128:131], v[30:33]
	v_mfma_f32_16x16x32_bf16 v[26:29], v[140:143], v[128:131], v[26:29]
	v_mfma_f32_16x16x32_bf16 v[18:21], v[144:147], v[128:131], v[18:21]
	s_waitcnt vmcnt(6) lgkmcnt(0)
	s_barrier
	ds_read_b128 v[116:119], v14
	ds_read_b128 v[120:123], v14 offset:2048
	ds_read_b128 v[124:127], v14 offset:4096
	ds_read_b128 v[128:131], v14 offset:6144
	ds_read_b128 v[132:135], v15
	ds_read_b128 v[136:139], v15 offset:2048
	ds_read_b128 v[140:143], v15 offset:4096
	ds_read_b128 v[144:147], v15 offset:6144
	v_mfma_f32_16x16x32_bf16 v[80:83], v[100:103], v[72:75], v[80:83]
	v_mfma_f32_16x16x32_bf16 v[84:87], v[104:107], v[72:75], v[84:87]
	v_mfma_f32_16x16x32_bf16 v[88:91], v[108:111], v[72:75], v[88:91]
	v_mfma_f32_16x16x32_bf16 v[22:25], v[112:115], v[72:75], v[22:25]
	v_mfma_f32_16x16x32_bf16 v[38:41], v[100:103], v[76:79], v[38:41]
	v_mfma_f32_16x16x32_bf16 v[46:49], v[104:107], v[76:79], v[46:49]
	v_mfma_f32_16x16x32_bf16 v[58:61], v[108:111], v[76:79], v[58:61]
	v_mfma_f32_16x16x32_bf16 v[50:53], v[112:115], v[76:79], v[50:53]
	v_mfma_f32_16x16x32_bf16 v[42:45], v[100:103], v[92:95], v[42:45]
	v_mfma_f32_16x16x32_bf16 v[62:65], v[104:107], v[92:95], v[62:65]
	v_mfma_f32_16x16x32_bf16 v[68:71], v[108:111], v[92:95], v[68:71]
	v_mfma_f32_16x16x32_bf16 v[54:57], v[112:115], v[92:95], v[54:57]
	v_mfma_f32_16x16x32_bf16 v[34:37], v[100:103], v[96:99], v[34:37]
	v_mfma_f32_16x16x32_bf16 v[30:33], v[104:107], v[96:99], v[30:33]
	v_mfma_f32_16x16x32_bf16 v[26:29], v[108:111], v[96:99], v[26:29]
	v_mfma_f32_16x16x32_bf16 v[18:21], v[112:115], v[96:99], v[18:21]
	s_mov_b32 m0, s66
	v_lshl_add_u64 v[72:73], v[4:5], 0, s[24:25]
	global_load_lds_dwordx4 v[72:73], off
	v_lshl_add_u64 v[72:73], v[6:7], 0, s[24:25]
	s_mov_b32 m0, s65
	s_mov_b64 s[76:77], 0x4000500
	global_load_lds_dwordx4 v[72:73], off
	v_lshl_add_u64 v[72:73], v[2:3], 0, s[76:77]
	s_mov_b32 m0, s4
	s_mov_b64 s[76:77], 0x4020500
	global_load_lds_dwordx4 v[72:73], off
	v_lshl_add_u64 v[72:73], v[2:3], 0, s[76:77]
	s_mov_b32 m0, s5
	s_mov_b64 s[76:77], 0x4040500
	global_load_lds_dwordx4 v[72:73], off
	v_lshl_add_u64 v[72:73], v[2:3], 0, s[76:77]
	s_mov_b32 m0, s67
	s_mov_b64 s[76:77], 0x4060500
	global_load_lds_dwordx4 v[72:73], off
	v_lshl_add_u64 v[72:73], v[2:3], 0, s[76:77]
	s_mov_b32 m0, s68
	s_nop 0
	global_load_lds_dwordx4 v[72:73], off
	ds_read_b128 v[72:75], v16
	ds_read_b128 v[76:79], v16 offset:2048
	ds_read_b128 v[92:95], v16 offset:4096
	ds_read_b128 v[96:99], v16 offset:6144
	ds_read_b128 v[100:103], v17
	ds_read_b128 v[104:107], v17 offset:2048
	ds_read_b128 v[108:111], v17 offset:4096
	ds_read_b128 v[112:115], v17 offset:6144
	s_waitcnt lgkmcnt(8)
	v_mfma_f32_16x16x32_bf16 v[80:83], v[132:135], v[116:119], v[80:83]
	v_mfma_f32_16x16x32_bf16 v[84:87], v[136:139], v[116:119], v[84:87]
	v_mfma_f32_16x16x32_bf16 v[88:91], v[140:143], v[116:119], v[88:91]
	v_mfma_f32_16x16x32_bf16 v[22:25], v[144:147], v[116:119], v[22:25]
	v_mfma_f32_16x16x32_bf16 v[38:41], v[132:135], v[120:123], v[38:41]
	v_mfma_f32_16x16x32_bf16 v[46:49], v[136:139], v[120:123], v[46:49]
	v_mfma_f32_16x16x32_bf16 v[58:61], v[140:143], v[120:123], v[58:61]
	v_mfma_f32_16x16x32_bf16 v[50:53], v[144:147], v[120:123], v[50:53]
	v_mfma_f32_16x16x32_bf16 v[42:45], v[132:135], v[124:127], v[42:45]
	v_mfma_f32_16x16x32_bf16 v[62:65], v[136:139], v[124:127], v[62:65]
	v_mfma_f32_16x16x32_bf16 v[68:71], v[140:143], v[124:127], v[68:71]
	v_mfma_f32_16x16x32_bf16 v[54:57], v[144:147], v[124:127], v[54:57]
	v_mfma_f32_16x16x32_bf16 v[34:37], v[132:135], v[128:131], v[34:37]
	v_mfma_f32_16x16x32_bf16 v[30:33], v[136:139], v[128:131], v[30:33]
	v_mfma_f32_16x16x32_bf16 v[26:29], v[140:143], v[128:131], v[26:29]
	v_mfma_f32_16x16x32_bf16 v[18:21], v[144:147], v[128:131], v[18:21]
	s_waitcnt vmcnt(6) lgkmcnt(0)
	s_barrier
	ds_read_b128 v[116:119], v8
	ds_read_b128 v[120:123], v8 offset:2048
	ds_read_b128 v[124:127], v8 offset:4096
	ds_read_b128 v[128:131], v8 offset:6144
	ds_read_b128 v[132:135], v9 offset:16384
	ds_read_b128 v[136:139], v9 offset:18432
	ds_read_b128 v[140:143], v9 offset:20480
	ds_read_b128 v[144:147], v9 offset:22528
	v_mfma_f32_16x16x32_bf16 v[80:83], v[100:103], v[72:75], v[80:83]
	v_mfma_f32_16x16x32_bf16 v[84:87], v[104:107], v[72:75], v[84:87]
	v_mfma_f32_16x16x32_bf16 v[88:91], v[108:111], v[72:75], v[88:91]
	v_mfma_f32_16x16x32_bf16 v[22:25], v[112:115], v[72:75], v[22:25]
	v_mfma_f32_16x16x32_bf16 v[38:41], v[100:103], v[76:79], v[38:41]
	v_mfma_f32_16x16x32_bf16 v[46:49], v[104:107], v[76:79], v[46:49]
	v_mfma_f32_16x16x32_bf16 v[58:61], v[108:111], v[76:79], v[58:61]
	v_mfma_f32_16x16x32_bf16 v[50:53], v[112:115], v[76:79], v[50:53]
	v_mfma_f32_16x16x32_bf16 v[42:45], v[100:103], v[92:95], v[42:45]
	v_mfma_f32_16x16x32_bf16 v[62:65], v[104:107], v[92:95], v[62:65]
	v_mfma_f32_16x16x32_bf16 v[68:71], v[108:111], v[92:95], v[68:71]
	v_mfma_f32_16x16x32_bf16 v[54:57], v[112:115], v[92:95], v[54:57]
	v_mfma_f32_16x16x32_bf16 v[34:37], v[100:103], v[96:99], v[34:37]
	v_mfma_f32_16x16x32_bf16 v[30:33], v[104:107], v[96:99], v[30:33]
	v_mfma_f32_16x16x32_bf16 v[26:29], v[108:111], v[96:99], v[26:29]
	v_mfma_f32_16x16x32_bf16 v[18:21], v[112:115], v[96:99], v[18:21]
	s_mov_b32 m0, s69
	v_lshl_add_u64 v[72:73], v[4:5], 0, s[26:27]
	global_load_lds_dwordx4 v[72:73], off
	v_lshl_add_u64 v[72:73], v[6:7], 0, s[26:27]
	s_mov_b32 m0, s70
	s_mov_b64 s[76:77], 0x4000580
	global_load_lds_dwordx4 v[72:73], off
	v_lshl_add_u64 v[72:73], v[2:3], 0, s[76:77]
	s_mov_b32 m0, s71
	s_mov_b64 s[76:77], 0x4020580
	global_load_lds_dwordx4 v[72:73], off
	v_lshl_add_u64 v[72:73], v[2:3], 0, s[76:77]
	s_mov_b32 m0, s72
	s_mov_b64 s[76:77], 0x4040580
	global_load_lds_dwordx4 v[72:73], off
	v_lshl_add_u64 v[72:73], v[2:3], 0, s[76:77]
	s_mov_b32 m0, s73
	s_mov_b64 s[76:77], 0x4060580
	global_load_lds_dwordx4 v[72:73], off
	v_lshl_add_u64 v[72:73], v[2:3], 0, s[76:77]
	s_mov_b32 m0, s74
	s_nop 0
	global_load_lds_dwordx4 v[72:73], off
	ds_read_b128 v[72:75], v10
	ds_read_b128 v[76:79], v10 offset:2048
	ds_read_b128 v[92:95], v10 offset:4096
	ds_read_b128 v[96:99], v10 offset:6144
	ds_read_b128 v[100:103], v11 offset:16384
	ds_read_b128 v[104:107], v11 offset:18432
	ds_read_b128 v[108:111], v11 offset:20480
	ds_read_b128 v[112:115], v11 offset:22528
	s_waitcnt lgkmcnt(8)
	v_mfma_f32_16x16x32_bf16 v[80:83], v[132:135], v[116:119], v[80:83]
	v_mfma_f32_16x16x32_bf16 v[84:87], v[136:139], v[116:119], v[84:87]
	v_mfma_f32_16x16x32_bf16 v[88:91], v[140:143], v[116:119], v[88:91]
	v_mfma_f32_16x16x32_bf16 v[22:25], v[144:147], v[116:119], v[22:25]
	v_mfma_f32_16x16x32_bf16 v[38:41], v[132:135], v[120:123], v[38:41]
	v_mfma_f32_16x16x32_bf16 v[46:49], v[136:139], v[120:123], v[46:49]
	v_mfma_f32_16x16x32_bf16 v[58:61], v[140:143], v[120:123], v[58:61]
	v_mfma_f32_16x16x32_bf16 v[50:53], v[144:147], v[120:123], v[50:53]
	v_mfma_f32_16x16x32_bf16 v[42:45], v[132:135], v[124:127], v[42:45]
	v_mfma_f32_16x16x32_bf16 v[62:65], v[136:139], v[124:127], v[62:65]
	v_mfma_f32_16x16x32_bf16 v[68:71], v[140:143], v[124:127], v[68:71]
	v_mfma_f32_16x16x32_bf16 v[54:57], v[144:147], v[124:127], v[54:57]
	v_mfma_f32_16x16x32_bf16 v[34:37], v[132:135], v[128:131], v[34:37]
	v_mfma_f32_16x16x32_bf16 v[30:33], v[136:139], v[128:131], v[30:33]
	v_mfma_f32_16x16x32_bf16 v[26:29], v[140:143], v[128:131], v[26:29]
	v_mfma_f32_16x16x32_bf16 v[18:21], v[144:147], v[128:131], v[18:21]
	s_waitcnt vmcnt(6) lgkmcnt(0)
	s_barrier
	ds_read_b128 v[116:119], v8 offset:49152
	ds_read_b128 v[120:123], v8 offset:51200
	ds_read_b128 v[124:127], v8 offset:53248
	ds_read_b128 v[128:131], v8 offset:55296
	ds_read_b128 v[132:135], v12
	ds_read_b128 v[136:139], v12 offset:2048
	ds_read_b128 v[140:143], v12 offset:4096
	ds_read_b128 v[144:147], v12 offset:6144
	v_mfma_f32_16x16x32_bf16 v[80:83], v[100:103], v[72:75], v[80:83]
	v_mfma_f32_16x16x32_bf16 v[84:87], v[104:107], v[72:75], v[84:87]
	v_mfma_f32_16x16x32_bf16 v[88:91], v[108:111], v[72:75], v[88:91]
	v_mfma_f32_16x16x32_bf16 v[22:25], v[112:115], v[72:75], v[22:25]
	v_mfma_f32_16x16x32_bf16 v[38:41], v[100:103], v[76:79], v[38:41]
	v_mfma_f32_16x16x32_bf16 v[46:49], v[104:107], v[76:79], v[46:49]
	v_mfma_f32_16x16x32_bf16 v[58:61], v[108:111], v[76:79], v[58:61]
	v_mfma_f32_16x16x32_bf16 v[50:53], v[112:115], v[76:79], v[50:53]
	v_mfma_f32_16x16x32_bf16 v[42:45], v[100:103], v[92:95], v[42:45]
	v_mfma_f32_16x16x32_bf16 v[62:65], v[104:107], v[92:95], v[62:65]
	v_mfma_f32_16x16x32_bf16 v[68:71], v[108:111], v[92:95], v[68:71]
	v_mfma_f32_16x16x32_bf16 v[54:57], v[112:115], v[92:95], v[54:57]
	v_mfma_f32_16x16x32_bf16 v[34:37], v[100:103], v[96:99], v[34:37]
	v_mfma_f32_16x16x32_bf16 v[30:33], v[104:107], v[96:99], v[30:33]
	v_mfma_f32_16x16x32_bf16 v[26:29], v[108:111], v[96:99], v[26:29]
	v_mfma_f32_16x16x32_bf16 v[18:21], v[112:115], v[96:99], v[18:21]
	s_mov_b32 m0, s64
	v_lshl_add_u64 v[72:73], v[4:5], 0, s[28:29]
	global_load_lds_dwordx4 v[72:73], off
	v_lshl_add_u64 v[72:73], v[6:7], 0, s[28:29]
	s_mov_b32 m0, s2
	s_mov_b64 s[76:77], 0x4000600
	global_load_lds_dwordx4 v[72:73], off
	v_lshl_add_u64 v[72:73], v[2:3], 0, s[76:77]
	s_mov_b32 m0, s33
	s_mov_b64 s[76:77], 0x4020600
	global_load_lds_dwordx4 v[72:73], off
	v_lshl_add_u64 v[72:73], v[2:3], 0, s[76:77]
	s_mov_b32 m0, s61
	s_mov_b64 s[76:77], 0x4040600
	global_load_lds_dwordx4 v[72:73], off
	v_lshl_add_u64 v[72:73], v[2:3], 0, s[76:77]
	s_mov_b32 m0, s62
	s_mov_b64 s[76:77], 0x4060600
	global_load_lds_dwordx4 v[72:73], off
	v_lshl_add_u64 v[72:73], v[2:3], 0, s[76:77]
	s_mov_b32 m0, s63
	s_nop 0
	global_load_lds_dwordx4 v[72:73], off
	ds_read_b128 v[72:75], v10 offset:49152
	ds_read_b128 v[76:79], v10 offset:51200
	ds_read_b128 v[92:95], v10 offset:53248
	ds_read_b128 v[96:99], v10 offset:55296
	ds_read_b128 v[100:103], v13
	ds_read_b128 v[104:107], v13 offset:2048
	ds_read_b128 v[108:111], v13 offset:4096
	ds_read_b128 v[112:115], v13 offset:6144
	s_waitcnt lgkmcnt(8)
	v_mfma_f32_16x16x32_bf16 v[80:83], v[132:135], v[116:119], v[80:83]
	v_mfma_f32_16x16x32_bf16 v[84:87], v[136:139], v[116:119], v[84:87]
	v_mfma_f32_16x16x32_bf16 v[88:91], v[140:143], v[116:119], v[88:91]
	v_mfma_f32_16x16x32_bf16 v[22:25], v[144:147], v[116:119], v[22:25]
	v_mfma_f32_16x16x32_bf16 v[38:41], v[132:135], v[120:123], v[38:41]
	v_mfma_f32_16x16x32_bf16 v[46:49], v[136:139], v[120:123], v[46:49]
	v_mfma_f32_16x16x32_bf16 v[58:61], v[140:143], v[120:123], v[58:61]
	v_mfma_f32_16x16x32_bf16 v[50:53], v[144:147], v[120:123], v[50:53]
	v_mfma_f32_16x16x32_bf16 v[42:45], v[132:135], v[124:127], v[42:45]
	v_mfma_f32_16x16x32_bf16 v[62:65], v[136:139], v[124:127], v[62:65]
	v_mfma_f32_16x16x32_bf16 v[68:71], v[140:143], v[124:127], v[68:71]
	v_mfma_f32_16x16x32_bf16 v[54:57], v[144:147], v[124:127], v[54:57]
	v_mfma_f32_16x16x32_bf16 v[34:37], v[132:135], v[128:131], v[34:37]
	v_mfma_f32_16x16x32_bf16 v[30:33], v[136:139], v[128:131], v[30:33]
	v_mfma_f32_16x16x32_bf16 v[26:29], v[140:143], v[128:131], v[26:29]
	v_mfma_f32_16x16x32_bf16 v[18:21], v[144:147], v[128:131], v[18:21]
	s_waitcnt vmcnt(6) lgkmcnt(0)
	s_barrier
	s_lshr_b32 s32, s39, 7
	s_add_i32 s32, s98, s32
	s_cmpk_ge_i32 s32, 0x800
	s_cbranch_scc1 .Lpf15_p1_skip
	s_mov_b32 s57, s32
	s_cmp_lg_u32 s39, 0x8000
	s_cbranch_scc1 .Lpf15_p1_nomap
	s_lshr_b32 s75, s32, 8
	s_bfe_u32 s76, s32, 0x30005
	s_and_b32 s77, s32, 31
	s_lshr_b32 s78, s75, 2
	s_lshl_b32 s78, s78, 3
	s_add_i32 s76, s76, s78
	s_and_b32 s75, s75, 3
	s_lshr_b32 s78, s75, 1
	s_xor_b32 s75, s75, s78
	s_and_b32 s75, s75, 1
	s_lshl_b32 s78, s78, 3
	s_lshr_b32 s79, s77, 2
	s_add_i32 s78, s78, s79
	s_and_b32 s77, s77, 3
	s_lshl_b32 s75, s75, 2
	s_add_i32 s75, s75, s77
	s_lshl_b32 s76, s76, 7
	s_lshl_b32 s75, s75, 4
	s_add_i32 s76, s76, s75
	s_add_i32 s57, s76, s78
.Lpf15_p1_nomap:
	s_ashr_i32 s75, s57, 7
	s_bfe_u32 s76, s57, 0x20002
	s_lshl_b32 s76, s76, 4
	s_add_i32 s76, s76, s75
	s_lshl_b32 s76, s76, 9
	s_lshl_b32 s77, s57, 7
	s_and_b32 s77, s77, 0x180
	s_or_b32 s76, s76, s77
	v_ashrrev_i32_e32 v202, 3, v0
	v_add_u32_e32 v204, s76, v202
	v_ashrrev_i32_e32 v205, 31, v204
	v_lshl_add_u64 v[204:205], v[204:205], 2, s[52:53]
	global_load_dword v200, v[204:205], off
	global_load_dword v201, v[204:205], off offset:256
.Lpf15_p1_skip:
	ds_read_b128 v[116:119], v14
	ds_read_b128 v[120:123], v14 offset:2048
	ds_read_b128 v[124:127], v14 offset:4096
	ds_read_b128 v[128:131], v14 offset:6144
	ds_read_b128 v[132:135], v15
	ds_read_b128 v[136:139], v15 offset:2048
	ds_read_b128 v[140:143], v15 offset:4096
	ds_read_b128 v[144:147], v15 offset:6144
	v_mfma_f32_16x16x32_bf16 v[80:83], v[100:103], v[72:75], v[80:83]
	v_mfma_f32_16x16x32_bf16 v[84:87], v[104:107], v[72:75], v[84:87]
	v_mfma_f32_16x16x32_bf16 v[88:91], v[108:111], v[72:75], v[88:91]
	v_mfma_f32_16x16x32_bf16 v[22:25], v[112:115], v[72:75], v[22:25]
	v_mfma_f32_16x16x32_bf16 v[38:41], v[100:103], v[76:79], v[38:41]
	v_mfma_f32_16x16x32_bf16 v[46:49], v[104:107], v[76:79], v[46:49]
	v_mfma_f32_16x16x32_bf16 v[58:61], v[108:111], v[76:79], v[58:61]
	v_mfma_f32_16x16x32_bf16 v[50:53], v[112:115], v[76:79], v[50:53]
	v_mfma_f32_16x16x32_bf16 v[42:45], v[100:103], v[92:95], v[42:45]
	v_mfma_f32_16x16x32_bf16 v[62:65], v[104:107], v[92:95], v[62:65]
	v_mfma_f32_16x16x32_bf16 v[68:71], v[108:111], v[92:95], v[68:71]
	v_mfma_f32_16x16x32_bf16 v[54:57], v[112:115], v[92:95], v[54:57]
	v_mfma_f32_16x16x32_bf16 v[34:37], v[100:103], v[96:99], v[34:37]
	v_mfma_f32_16x16x32_bf16 v[30:33], v[104:107], v[96:99], v[30:33]
	v_mfma_f32_16x16x32_bf16 v[26:29], v[108:111], v[96:99], v[26:29]
	v_mfma_f32_16x16x32_bf16 v[18:21], v[112:115], v[96:99], v[18:21]
	s_mov_b32 m0, s66
	v_lshl_add_u64 v[72:73], v[4:5], 0, s[30:31]
	global_load_lds_dwordx4 v[72:73], off
	v_lshl_add_u64 v[72:73], v[6:7], 0, s[30:31]
	s_mov_b32 m0, s65
	s_mov_b64 s[76:77], 0x4000680
	global_load_lds_dwordx4 v[72:73], off
	v_lshl_add_u64 v[72:73], v[2:3], 0, s[76:77]
	s_mov_b32 m0, s4
	s_mov_b64 s[76:77], 0x4020680
	global_load_lds_dwordx4 v[72:73], off
	v_lshl_add_u64 v[72:73], v[2:3], 0, s[76:77]
	s_mov_b32 m0, s5
	s_mov_b64 s[4:5], 0x4040680
	global_load_lds_dwordx4 v[72:73], off
	v_lshl_add_u64 v[72:73], v[2:3], 0, s[4:5]
	v_readlane_b32 s4, v196, 22
	v_readlane_b32 s5, v196, 23
	s_mov_b32 m0, s67
	s_mov_b32 s10, s4
	s_mov_b64 s[4:5], 0x4060680
	global_load_lds_dwordx4 v[72:73], off
	v_lshl_add_u64 v[72:73], v[2:3], 0, s[4:5]
	s_mov_b32 m0, s68
	s_nop 0
	global_load_lds_dwordx4 v[72:73], off
	ds_read_b128 v[72:75], v16
	ds_read_b128 v[76:79], v16 offset:2048
	ds_read_b128 v[92:95], v16 offset:4096
	ds_read_b128 v[96:99], v16 offset:6144
	ds_read_b128 v[100:103], v17
	ds_read_b128 v[104:107], v17 offset:2048
	ds_read_b128 v[108:111], v17 offset:4096
	ds_read_b128 v[112:115], v17 offset:6144
	s_waitcnt lgkmcnt(8)
	v_mfma_f32_16x16x32_bf16 v[80:83], v[132:135], v[116:119], v[80:83]
	v_mfma_f32_16x16x32_bf16 v[84:87], v[136:139], v[116:119], v[84:87]
	v_mfma_f32_16x16x32_bf16 v[88:91], v[140:143], v[116:119], v[88:91]
	v_mfma_f32_16x16x32_bf16 v[22:25], v[144:147], v[116:119], v[22:25]
	v_mfma_f32_16x16x32_bf16 v[38:41], v[132:135], v[120:123], v[38:41]
	v_mfma_f32_16x16x32_bf16 v[46:49], v[136:139], v[120:123], v[46:49]
	v_mfma_f32_16x16x32_bf16 v[58:61], v[140:143], v[120:123], v[58:61]
	v_mfma_f32_16x16x32_bf16 v[50:53], v[144:147], v[120:123], v[50:53]
	v_mfma_f32_16x16x32_bf16 v[42:45], v[132:135], v[124:127], v[42:45]
	v_mfma_f32_16x16x32_bf16 v[62:65], v[136:139], v[124:127], v[62:65]
	v_mfma_f32_16x16x32_bf16 v[68:71], v[140:143], v[124:127], v[68:71]
	v_mfma_f32_16x16x32_bf16 v[54:57], v[144:147], v[124:127], v[54:57]
	v_mfma_f32_16x16x32_bf16 v[34:37], v[132:135], v[128:131], v[34:37]
	v_mfma_f32_16x16x32_bf16 v[30:33], v[136:139], v[128:131], v[30:33]
	v_mfma_f32_16x16x32_bf16 v[26:29], v[140:143], v[128:131], v[26:29]
	v_mfma_f32_16x16x32_bf16 v[18:21], v[144:147], v[128:131], v[18:21]
	s_waitcnt vmcnt(6) lgkmcnt(0)
	s_barrier
	ds_read_b128 v[116:119], v8
	ds_read_b128 v[120:123], v8 offset:2048
	ds_read_b128 v[124:127], v8 offset:4096
	ds_read_b128 v[128:131], v8 offset:6144
	ds_read_b128 v[132:135], v9 offset:16384
	ds_read_b128 v[136:139], v9 offset:18432
	ds_read_b128 v[140:143], v9 offset:20480
	ds_read_b128 v[144:147], v9 offset:22528
	v_mfma_f32_16x16x32_bf16 v[80:83], v[100:103], v[72:75], v[80:83]
	v_mfma_f32_16x16x32_bf16 v[84:87], v[104:107], v[72:75], v[84:87]
	v_mfma_f32_16x16x32_bf16 v[88:91], v[108:111], v[72:75], v[88:91]
	v_mfma_f32_16x16x32_bf16 v[22:25], v[112:115], v[72:75], v[22:25]
	v_mfma_f32_16x16x32_bf16 v[38:41], v[100:103], v[76:79], v[38:41]
	v_mfma_f32_16x16x32_bf16 v[46:49], v[104:107], v[76:79], v[46:49]
	v_mfma_f32_16x16x32_bf16 v[58:61], v[108:111], v[76:79], v[58:61]
	v_mfma_f32_16x16x32_bf16 v[50:53], v[112:115], v[76:79], v[50:53]
	v_mfma_f32_16x16x32_bf16 v[42:45], v[100:103], v[92:95], v[42:45]
	v_mfma_f32_16x16x32_bf16 v[62:65], v[104:107], v[92:95], v[62:65]
	v_mfma_f32_16x16x32_bf16 v[68:71], v[108:111], v[92:95], v[68:71]
	v_mfma_f32_16x16x32_bf16 v[54:57], v[112:115], v[92:95], v[54:57]
	v_mfma_f32_16x16x32_bf16 v[34:37], v[100:103], v[96:99], v[34:37]
	v_mfma_f32_16x16x32_bf16 v[30:33], v[104:107], v[96:99], v[30:33]
	v_mfma_f32_16x16x32_bf16 v[26:29], v[108:111], v[96:99], v[26:29]
	v_mfma_f32_16x16x32_bf16 v[18:21], v[112:115], v[96:99], v[18:21]
	s_mov_b32 m0, s69
	v_lshl_add_u64 v[72:73], v[4:5], 0, s[34:35]
	global_load_lds_dwordx4 v[72:73], off
	v_lshl_add_u64 v[72:73], v[6:7], 0, s[34:35]
	s_mov_b32 m0, s70
	s_mov_b64 s[4:5], 0x4000700
	global_load_lds_dwordx4 v[72:73], off
	v_lshl_add_u64 v[72:73], v[2:3], 0, s[4:5]
	s_mov_b32 m0, s71
	s_mov_b64 s[4:5], 0x4020700
	global_load_lds_dwordx4 v[72:73], off
	v_lshl_add_u64 v[72:73], v[2:3], 0, s[4:5]
	s_mov_b32 m0, s72
	s_mov_b64 s[4:5], 0x4040700
	global_load_lds_dwordx4 v[72:73], off
	v_lshl_add_u64 v[72:73], v[2:3], 0, s[4:5]
	s_mov_b32 m0, s73
	s_mov_b64 s[4:5], 0x4060700
	global_load_lds_dwordx4 v[72:73], off
	v_lshl_add_u64 v[72:73], v[2:3], 0, s[4:5]
	s_mov_b32 m0, s74
	v_readlane_b32 s72, v197, 34
	global_load_lds_dwordx4 v[72:73], off
	ds_read_b128 v[72:75], v10
	ds_read_b128 v[76:79], v10 offset:2048
	ds_read_b128 v[92:95], v10 offset:4096
	ds_read_b128 v[96:99], v10 offset:6144
	ds_read_b128 v[100:103], v11 offset:16384
	ds_read_b128 v[104:107], v11 offset:18432
	ds_read_b128 v[108:111], v11 offset:20480
	ds_read_b128 v[112:115], v11 offset:22528
	v_readlane_b32 s73, v197, 35
	v_readlane_b32 s82, v197, 44
	v_readlane_b32 s83, v197, 45
	v_readlane_b32 s84, v197, 46
	v_readlane_b32 s85, v197, 47
	v_readlane_b32 s74, v197, 36
	v_readlane_b32 s75, v197, 37
	v_readlane_b32 s76, v197, 38
	v_readlane_b32 s77, v197, 39
	v_readlane_b32 s78, v197, 40
	v_readlane_b32 s79, v197, 41
	v_readlane_b32 s80, v197, 42
	v_readlane_b32 s81, v197, 43
	v_readlane_b32 s86, v197, 48
	v_readlane_b32 s87, v197, 49
	s_waitcnt lgkmcnt(8)
	v_mfma_f32_16x16x32_bf16 v[80:83], v[132:135], v[116:119], v[80:83]
	v_mfma_f32_16x16x32_bf16 v[84:87], v[136:139], v[116:119], v[84:87]
	v_mfma_f32_16x16x32_bf16 v[88:91], v[140:143], v[116:119], v[88:91]
	v_mfma_f32_16x16x32_bf16 v[22:25], v[144:147], v[116:119], v[22:25]
	v_mfma_f32_16x16x32_bf16 v[38:41], v[132:135], v[120:123], v[38:41]
	v_mfma_f32_16x16x32_bf16 v[46:49], v[136:139], v[120:123], v[46:49]
	v_mfma_f32_16x16x32_bf16 v[58:61], v[140:143], v[120:123], v[58:61]
	v_mfma_f32_16x16x32_bf16 v[50:53], v[144:147], v[120:123], v[50:53]
	v_mfma_f32_16x16x32_bf16 v[42:45], v[132:135], v[124:127], v[42:45]
	v_mfma_f32_16x16x32_bf16 v[62:65], v[136:139], v[124:127], v[62:65]
	v_mfma_f32_16x16x32_bf16 v[68:71], v[140:143], v[124:127], v[68:71]
	v_mfma_f32_16x16x32_bf16 v[54:57], v[144:147], v[124:127], v[54:57]
	v_mfma_f32_16x16x32_bf16 v[34:37], v[132:135], v[128:131], v[34:37]
	v_mfma_f32_16x16x32_bf16 v[30:33], v[136:139], v[128:131], v[30:33]
	v_mfma_f32_16x16x32_bf16 v[26:29], v[140:143], v[128:131], v[26:29]
	v_mfma_f32_16x16x32_bf16 v[18:21], v[144:147], v[128:131], v[18:21]
	s_waitcnt vmcnt(6) lgkmcnt(0)
	s_barrier
	ds_read_b128 v[116:119], v8 offset:49152
	ds_read_b128 v[120:123], v8 offset:51200
	ds_read_b128 v[124:127], v8 offset:53248
	ds_read_b128 v[128:131], v8 offset:55296
	ds_read_b128 v[132:135], v12
	ds_read_b128 v[136:139], v12 offset:2048
	ds_read_b128 v[140:143], v12 offset:4096
	ds_read_b128 v[144:147], v12 offset:6144
	v_mfma_f32_16x16x32_bf16 v[80:83], v[100:103], v[72:75], v[80:83]
	v_mfma_f32_16x16x32_bf16 v[84:87], v[104:107], v[72:75], v[84:87]
	v_mfma_f32_16x16x32_bf16 v[88:91], v[108:111], v[72:75], v[88:91]
	v_mfma_f32_16x16x32_bf16 v[22:25], v[112:115], v[72:75], v[22:25]
	v_mfma_f32_16x16x32_bf16 v[38:41], v[100:103], v[76:79], v[38:41]
	v_mfma_f32_16x16x32_bf16 v[46:49], v[104:107], v[76:79], v[46:49]
	v_mfma_f32_16x16x32_bf16 v[58:61], v[108:111], v[76:79], v[58:61]
	v_mfma_f32_16x16x32_bf16 v[50:53], v[112:115], v[76:79], v[50:53]
	v_mfma_f32_16x16x32_bf16 v[42:45], v[100:103], v[92:95], v[42:45]
	v_mfma_f32_16x16x32_bf16 v[62:65], v[104:107], v[92:95], v[62:65]
	v_mfma_f32_16x16x32_bf16 v[68:71], v[108:111], v[92:95], v[68:71]
	v_mfma_f32_16x16x32_bf16 v[54:57], v[112:115], v[92:95], v[54:57]
	v_mfma_f32_16x16x32_bf16 v[34:37], v[100:103], v[96:99], v[34:37]
	v_mfma_f32_16x16x32_bf16 v[30:33], v[104:107], v[96:99], v[30:33]
	v_mfma_f32_16x16x32_bf16 v[26:29], v[108:111], v[96:99], v[26:29]
	v_mfma_f32_16x16x32_bf16 v[18:21], v[112:115], v[96:99], v[18:21]
	s_mov_b32 m0, s64
	v_lshl_add_u64 v[4:5], v[4:5], 0, s[36:37]
	global_load_lds_dwordx4 v[4:5], off
	v_lshl_add_u64 v[4:5], v[6:7], 0, s[36:37]
	s_mov_b32 m0, s2
	s_mov_b64 s[4:5], 0x4060780
	global_load_lds_dwordx4 v[4:5], off
	v_lshl_add_u64 v[4:5], v[2:3], 0, s[16:17]
	s_mov_b32 m0, s33
	s_nop 0
	global_load_lds_dwordx4 v[4:5], off
	v_lshl_add_u64 v[4:5], v[2:3], 0, s[18:19]
	s_mov_b32 m0, s61
	s_nop 0
	global_load_lds_dwordx4 v[4:5], off
	v_lshl_add_u64 v[4:5], v[2:3], 0, s[20:21]
	s_mov_b32 m0, s62
	v_lshl_add_u64 v[2:3], v[2:3], 0, s[4:5]
	global_load_lds_dwordx4 v[4:5], off
	s_mov_b32 m0, s63
	s_nop 0
	global_load_lds_dwordx4 v[2:3], off
	ds_read_b128 v[2:5], v10 offset:49152
	ds_read_b128 v[72:75], v10 offset:51200
	ds_read_b128 v[76:79], v10 offset:53248
	ds_read_b128 v[92:95], v10 offset:55296
	ds_read_b128 v[96:99], v13
	ds_read_b128 v[100:103], v13 offset:2048
	ds_read_b128 v[104:107], v13 offset:4096
	ds_read_b128 v[108:111], v13 offset:6144
	s_waitcnt lgkmcnt(8)
	v_mfma_f32_16x16x32_bf16 v[80:83], v[132:135], v[116:119], v[80:83]
	v_mfma_f32_16x16x32_bf16 v[84:87], v[136:139], v[116:119], v[84:87]
	v_mfma_f32_16x16x32_bf16 v[88:91], v[140:143], v[116:119], v[88:91]
	v_mfma_f32_16x16x32_bf16 v[22:25], v[144:147], v[116:119], v[22:25]
	v_mfma_f32_16x16x32_bf16 v[38:41], v[132:135], v[120:123], v[38:41]
	v_mfma_f32_16x16x32_bf16 v[46:49], v[136:139], v[120:123], v[46:49]
	v_mfma_f32_16x16x32_bf16 v[58:61], v[140:143], v[120:123], v[58:61]
	v_mfma_f32_16x16x32_bf16 v[50:53], v[144:147], v[120:123], v[50:53]
	v_mfma_f32_16x16x32_bf16 v[42:45], v[132:135], v[124:127], v[42:45]
	v_mfma_f32_16x16x32_bf16 v[62:65], v[136:139], v[124:127], v[62:65]
	v_mfma_f32_16x16x32_bf16 v[68:71], v[140:143], v[124:127], v[68:71]
	v_mfma_f32_16x16x32_bf16 v[54:57], v[144:147], v[124:127], v[54:57]
	v_mfma_f32_16x16x32_bf16 v[34:37], v[132:135], v[128:131], v[34:37]
	v_mfma_f32_16x16x32_bf16 v[30:33], v[136:139], v[128:131], v[30:33]
	v_mfma_f32_16x16x32_bf16 v[26:29], v[140:143], v[128:131], v[26:29]
	v_mfma_f32_16x16x32_bf16 v[18:21], v[144:147], v[128:131], v[18:21]
	s_waitcnt vmcnt(6) lgkmcnt(0)
	s_barrier
	ds_read_b128 v[112:115], v14
	ds_read_b128 v[116:119], v14 offset:2048
	ds_read_b128 v[120:123], v14 offset:4096
	ds_read_b128 v[124:127], v14 offset:6144
	ds_read_b128 v[128:131], v15
	ds_read_b128 v[132:135], v15 offset:2048
	ds_read_b128 v[136:139], v15 offset:4096
	ds_read_b128 v[12:15], v15 offset:6144
	v_mfma_f32_16x16x32_bf16 v[80:83], v[96:99], v[2:5], v[80:83]
	v_mfma_f32_16x16x32_bf16 v[84:87], v[100:103], v[2:5], v[84:87]
	v_mfma_f32_16x16x32_bf16 v[88:91], v[104:107], v[2:5], v[88:91]
	v_mfma_f32_16x16x32_bf16 v[2:5], v[108:111], v[2:5], v[22:25]
	v_mfma_f32_16x16x32_bf16 v[22:25], v[96:99], v[72:75], v[38:41]
	v_mfma_f32_16x16x32_bf16 v[38:41], v[100:103], v[72:75], v[46:49]
	v_mfma_f32_16x16x32_bf16 v[46:49], v[104:107], v[72:75], v[58:61]
	v_mfma_f32_16x16x32_bf16 v[50:53], v[108:111], v[72:75], v[50:53]
	v_mfma_f32_16x16x32_bf16 v[42:45], v[96:99], v[76:79], v[42:45]
	v_mfma_f32_16x16x32_bf16 v[58:61], v[100:103], v[76:79], v[62:65]
	v_mfma_f32_16x16x32_bf16 v[62:65], v[104:107], v[76:79], v[68:71]
	v_mfma_f32_16x16x32_bf16 v[54:57], v[108:111], v[76:79], v[54:57]
	v_mfma_f32_16x16x32_bf16 v[34:37], v[96:99], v[92:95], v[34:37]
	v_mfma_f32_16x16x32_bf16 v[30:33], v[100:103], v[92:95], v[30:33]
	v_mfma_f32_16x16x32_bf16 v[26:29], v[104:107], v[92:95], v[26:29]
	v_mfma_f32_16x16x32_bf16 v[18:21], v[108:111], v[92:95], v[18:21]
	ds_read_b128 v[68:71], v16
	ds_read_b128 v[72:75], v16 offset:2048
	ds_read_b128 v[76:79], v16 offset:4096
	ds_read_b128 v[92:95], v16 offset:6144
	ds_read_b128 v[96:99], v17
	ds_read_b128 v[100:103], v17 offset:2048
	ds_read_b128 v[104:107], v17 offset:4096
	ds_read_b128 v[108:111], v17 offset:6144
	s_waitcnt lgkmcnt(8)
	v_mfma_f32_16x16x32_bf16 v[80:83], v[128:131], v[112:115], v[80:83]
	v_mfma_f32_16x16x32_bf16 v[84:87], v[132:135], v[112:115], v[84:87]
	v_mfma_f32_16x16x32_bf16 v[88:91], v[136:139], v[112:115], v[88:91]
	v_mfma_f32_16x16x32_bf16 v[2:5], v[12:15], v[112:115], v[2:5]
	v_mfma_f32_16x16x32_bf16 v[22:25], v[128:131], v[116:119], v[22:25]
	v_mfma_f32_16x16x32_bf16 v[38:41], v[132:135], v[116:119], v[38:41]
	v_mfma_f32_16x16x32_bf16 v[46:49], v[136:139], v[116:119], v[46:49]
	v_mfma_f32_16x16x32_bf16 v[50:53], v[12:15], v[116:119], v[50:53]
	v_mfma_f32_16x16x32_bf16 v[42:45], v[128:131], v[120:123], v[42:45]
	v_mfma_f32_16x16x32_bf16 v[58:61], v[132:135], v[120:123], v[58:61]
	v_mfma_f32_16x16x32_bf16 v[62:65], v[136:139], v[120:123], v[62:65]
	v_mfma_f32_16x16x32_bf16 v[54:57], v[12:15], v[120:123], v[54:57]
	v_mfma_f32_16x16x32_bf16 v[34:37], v[128:131], v[124:127], v[34:37]
	v_mfma_f32_16x16x32_bf16 v[30:33], v[132:135], v[124:127], v[30:33]
	v_mfma_f32_16x16x32_bf16 v[26:29], v[136:139], v[124:127], v[26:29]
	v_mfma_f32_16x16x32_bf16 v[12:15], v[12:15], v[124:127], v[18:21]
	s_waitcnt vmcnt(0) lgkmcnt(0)
	s_barrier
	s_nop 1
	ds_read_b128 v[16:19], v8
	ds_read_b128 v[112:115], v8 offset:2048
	ds_read_b128 v[116:119], v8 offset:4096
	ds_read_b128 v[120:123], v8 offset:6144
	ds_read_b128 v[124:127], v9 offset:16384
	ds_read_b128 v[128:131], v9 offset:18432
	ds_read_b128 v[132:135], v9 offset:20480
	ds_read_b128 v[6:9], v9 offset:22528
	v_mfma_f32_16x16x32_bf16 v[80:83], v[96:99], v[68:71], v[80:83]
	v_mfma_f32_16x16x32_bf16 v[84:87], v[100:103], v[68:71], v[84:87]
	v_mfma_f32_16x16x32_bf16 v[88:91], v[104:107], v[68:71], v[88:91]
	v_mfma_f32_16x16x32_bf16 v[2:5], v[108:111], v[68:71], v[2:5]
	v_mfma_f32_16x16x32_bf16 v[20:23], v[96:99], v[72:75], v[22:25]
	v_mfma_f32_16x16x32_bf16 v[38:41], v[100:103], v[72:75], v[38:41]
	v_mfma_f32_16x16x32_bf16 v[46:49], v[104:107], v[72:75], v[46:49]
	v_mfma_f32_16x16x32_bf16 v[50:53], v[108:111], v[72:75], v[50:53]
	v_mfma_f32_16x16x32_bf16 v[42:45], v[96:99], v[76:79], v[42:45]
	v_mfma_f32_16x16x32_bf16 v[58:61], v[100:103], v[76:79], v[58:61]
	v_mfma_f32_16x16x32_bf16 v[62:65], v[104:107], v[76:79], v[62:65]
	v_mfma_f32_16x16x32_bf16 v[54:57], v[108:111], v[76:79], v[54:57]
	v_mfma_f32_16x16x32_bf16 v[34:37], v[96:99], v[92:95], v[34:37]
	v_mfma_f32_16x16x32_bf16 v[30:33], v[100:103], v[92:95], v[30:33]
	v_mfma_f32_16x16x32_bf16 v[24:27], v[104:107], v[92:95], v[26:29]
	v_mfma_f32_16x16x32_bf16 v[12:15], v[108:111], v[92:95], v[12:15]
	ds_read_b128 v[68:71], v10
	ds_read_b128 v[72:75], v10 offset:2048
	ds_read_b128 v[76:79], v10 offset:4096
	ds_read_b128 v[92:95], v10 offset:6144
	ds_read_b128 v[96:99], v11 offset:16384
	ds_read_b128 v[100:103], v11 offset:18432
	ds_read_b128 v[104:107], v11 offset:20480
	ds_read_b128 v[108:111], v11 offset:22528
	s_waitcnt lgkmcnt(8)
	v_mfma_f32_16x16x32_bf16 v[80:83], v[124:127], v[16:19], v[80:83]
	v_mfma_f32_16x16x32_bf16 v[84:87], v[128:131], v[16:19], v[84:87]
	v_mfma_f32_16x16x32_bf16 v[88:91], v[132:135], v[16:19], v[88:91]
	v_mfma_f32_16x16x32_bf16 v[2:5], v[6:9], v[16:19], v[2:5]
	v_mfma_f32_16x16x32_bf16 v[16:19], v[124:127], v[112:115], v[20:23]
	v_mfma_f32_16x16x32_bf16 v[20:23], v[128:131], v[112:115], v[38:41]
	v_mfma_f32_16x16x32_bf16 v[38:41], v[132:135], v[112:115], v[46:49]
	v_mfma_f32_16x16x32_bf16 v[112:115], v[6:9], v[112:115], v[50:53]
	v_mfma_f32_16x16x32_bf16 v[136:139], v[124:127], v[116:119], v[42:45]
	v_mfma_f32_16x16x32_bf16 v[140:143], v[128:131], v[116:119], v[58:61]
	v_mfma_f32_16x16x32_bf16 v[144:147], v[132:135], v[116:119], v[62:65]
	v_mfma_f32_16x16x32_bf16 v[116:119], v[6:9], v[116:119], v[54:57]
	v_mfma_f32_16x16x32_bf16 v[124:127], v[124:127], v[120:123], v[34:37]
	v_mfma_f32_16x16x32_bf16 v[128:131], v[128:131], v[120:123], v[30:33]
	v_mfma_f32_16x16x32_bf16 v[132:135], v[132:135], v[120:123], v[24:27]
	v_mfma_f32_16x16x32_bf16 v[120:123], v[6:9], v[120:123], v[12:15]
	s_waitcnt vmcnt(0) lgkmcnt(0)
	s_barrier
	v_mfma_f32_16x16x32_bf16 v[58:61], v[96:99], v[68:71], v[80:83]
	v_mfma_f32_16x16x32_bf16 v[62:65], v[100:103], v[68:71], v[84:87]
	v_mfma_f32_16x16x32_bf16 v[54:57], v[104:107], v[68:71], v[88:91]
	v_mfma_f32_16x16x32_bf16 v[50:53], v[108:111], v[68:71], v[2:5]
	v_mfma_f32_16x16x32_bf16 v[42:45], v[96:99], v[72:75], v[16:19]
	v_mfma_f32_16x16x32_bf16 v[46:49], v[100:103], v[72:75], v[20:23]
	v_mfma_f32_16x16x32_bf16 v[38:41], v[104:107], v[72:75], v[38:41]
	v_mfma_f32_16x16x32_bf16 v[34:37], v[108:111], v[72:75], v[112:115]
	v_mfma_f32_16x16x32_bf16 v[26:29], v[96:99], v[76:79], v[136:139]
	v_mfma_f32_16x16x32_bf16 v[30:33], v[100:103], v[76:79], v[140:143]
	v_mfma_f32_16x16x32_bf16 v[22:25], v[104:107], v[76:79], v[144:147]
	v_mfma_f32_16x16x32_bf16 v[18:21], v[108:111], v[76:79], v[116:119]
	v_mfma_f32_16x16x32_bf16 v[10:13], v[96:99], v[92:95], v[124:127]
	v_mfma_f32_16x16x32_bf16 v[14:17], v[100:103], v[92:95], v[128:131]
	v_mfma_f32_16x16x32_bf16 v[6:9], v[104:107], v[92:95], v[132:135]
	v_mfma_f32_16x16x32_bf16 v[2:5], v[108:111], v[92:95], v[120:123]
	v_ashrrev_i32_e32 v66, 2, v1
	v_and_b32_e32 v66, 0xffffffc0, v66
	v_add_u32_e32 v66, s59, v66
	v_and_or_b32 v68, v1, 15, v66
	v_mul_f32_e32 v66, 0xbfb8aa3b, v58
	v_exp_f32_e32 v72, v66
	v_mul_f32_e32 v66, 0xbfb8aa3b, v59
	v_exp_f32_e32 v73, v66
	s_ashr_i32 s59, s58, 31
	s_lshl_b64 s[4:5], s[58:59], 20
	v_lshrrev_b32_e32 v78, 1, v1
	v_pk_add_f32 v[76:77], v[72:73], 1.0 op_sel_hi:[1,0]
	v_ashrrev_i32_e32 v69, 31, v68
	s_add_u32 s4, s22, s4
	v_and_b32_e32 v66, 0xc0, v1
	v_div_scale_f32 v1, s[58:59], v77, v77, v59
	s_addc_u32 s5, s23, s5
	v_lshlrev_b64 v[70:71], 11, v[68:69]
	v_rcp_f32_e32 v69, v1
	v_lshl_add_u64 v[70:71], s[4:5], 0, v[70:71]
	s_lshl_b32 s2, s60, 8
	v_lshl_add_u64 v[70:71], v[70:71], 0, s[2:3]
	v_lshl_add_u64 v[74:75], v[70:71], 0, v[66:67]
	v_and_b32_e32 v70, 24, v78
	v_mov_b32_e32 v71, v67
	v_lshl_add_u64 v[72:73], v[74:75], 0, v[70:71]
	v_fma_f32 v74, -v1, v69, 1.0
	v_fmac_f32_e32 v69, v74, v69
	v_div_scale_f32 v74, vcc, v59, v77, v59
	v_mul_f32_e32 v75, v74, v69
	v_fma_f32 v78, -v1, v75, v74
	v_fmac_f32_e32 v75, v78, v69
	v_div_scale_f32 v78, s[58:59], v76, v76, v58
	v_rcp_f32_e32 v79, v78
	v_fma_f32 v1, -v1, v75, v74
	v_div_fmas_f32 v1, v1, v69, v75
	v_mul_f32_e32 v74, 0xbfb8aa3b, v60
	v_mul_f32_e32 v75, 0xbfb8aa3b, v61
	v_exp_f32_e32 v74, v74
	v_exp_f32_e32 v75, v75
	v_div_fixup_f32 v59, v1, v77, v59
	v_fma_f32 v1, -v78, v79, 1.0
	v_fmac_f32_e32 v79, v1, v79
	v_div_scale_f32 v1, vcc, v58, v76, v58
	v_mul_f32_e32 v69, v1, v79
	v_fma_f32 v77, -v78, v69, v1
	v_pk_add_f32 v[74:75], v[74:75], 1.0 op_sel_hi:[1,0]
	v_fmac_f32_e32 v69, v77, v79
	v_div_scale_f32 v77, s[58:59], v75, v75, v61
	v_fma_f32 v1, -v78, v69, v1
	v_rcp_f32_e32 v78, v77
	v_div_fmas_f32 v1, v1, v79, v69
	v_div_fixup_f32 v58, v1, v76, v58
	v_pk_mul_f32 v[58:59], v[62:63], v[58:59]
	v_fma_f32 v1, -v77, v78, 1.0
	v_fmac_f32_e32 v78, v1, v78
	v_div_scale_f32 v1, vcc, v61, v75, v61
	v_mul_f32_e32 v62, v1, v78
	v_fma_f32 v63, -v77, v62, v1
	v_fmac_f32_e32 v62, v63, v78
	v_div_scale_f32 v63, s[58:59], v74, v74, v60
	v_rcp_f32_e32 v69, v63
	v_fma_f32 v1, -v77, v62, v1
	v_div_fmas_f32 v1, v1, v78, v62
	v_div_fixup_f32 v61, v1, v75, v61
	v_fma_f32 v1, -v63, v69, 1.0
	v_fmac_f32_e32 v69, v1, v69
	v_div_scale_f32 v1, vcc, v60, v74, v60
	v_mul_f32_e32 v75, v1, v69
	v_fma_f32 v62, -v63, v75, v1
	v_fmac_f32_e32 v75, v62, v69
	v_fma_f32 v1, -v63, v75, v1
	v_mul_f32_e32 v62, 0xbfb8aa3b, v54
	v_mul_f32_e32 v63, 0xbfb8aa3b, v55
	v_exp_f32_e32 v62, v62
	v_exp_f32_e32 v63, v63
	v_div_fmas_f32 v1, v1, v69, v75
	v_div_fixup_f32 v60, v1, v74, v60
	v_pk_mul_f32 v[60:61], v[64:65], v[60:61]
	v_pk_add_f32 v[62:63], v[62:63], 1.0 op_sel_hi:[1,0]
	v_cvt_pk_bf16_f32 v58, v58, v59
	v_div_scale_f32 v1, s[58:59], v63, v63, v55
	v_rcp_f32_e32 v64, v1
	v_cvt_pk_bf16_f32 v59, v60, v61
	s_waitcnt lgkmcnt(0)
	s_barrier
	s_lshr_b32 s57, s39, 7
	s_add_i32 s57, s98, s57
	s_cmpk_ge_i32 s57, 0x800
	s_cbranch_scc1 .Lpf15_p2_skip
	s_mov_b32 s60, s57
	s_cmp_lg_u32 s39, 0x8000
	s_cbranch_scc1 .Lpf15_p2_nomap
	s_lshr_b32 s32, s57, 8
	s_bfe_u32 s33, s57, 0x30005
	s_and_b32 s58, s57, 31
	s_lshr_b32 s59, s32, 2
	s_lshl_b32 s59, s59, 3
	s_add_i32 s33, s33, s59
	s_and_b32 s32, s32, 3
	s_lshr_b32 s59, s32, 1
	s_xor_b32 s32, s32, s59
	s_and_b32 s32, s32, 1
	s_lshl_b32 s59, s59, 3
	s_lshr_b32 s61, s58, 2
	s_add_i32 s59, s59, s61
	s_and_b32 s58, s58, 3
	s_lshl_b32 s32, s32, 2
	s_add_i32 s32, s32, s58
	s_lshl_b32 s33, s33, 7
	s_lshl_b32 s32, s32, 4
	s_add_i32 s33, s33, s32
	s_add_i32 s60, s33, s59
.Lpf15_p2_nomap:
	s_ashr_i32 s32, s60, 7
	s_ashr_i32 s33, s32, 31
	s_lshl_b64 s[32:33], s[32:33], 22
	s_add_u32 s32, s82, s32
	s_addc_u32 s33, s83, s33
	s_bfe_u32 s58, s60, 0x30004
	s_lshl_b32 s58, s58, 19
	s_add_u32 s32, s32, s58
	s_addc_u32 s33, s33, 0
	s_bfe_u32 s58, s60, 0x20002
	s_lshl_b32 s58, s58, 12
	s_mov_b32 s59, 0
	v_ashrrev_i32_e32 v202, 3, v0
	v_lshrrev_b32_e32 v206, 4, v0
	v_xor_b32_e32 v206, v206, v0
	v_lshlrev_b32_e32 v206, 4, v206
	v_and_b32_e32 v206, 0x70, v206
	v_mov_b32_e32 v207, 0
	v_ashrrev_i32_e32 v203, 31, v202
	v_lshlrev_b64 v[202:203], 11, v[202:203]
	v_lshl_add_u64 v[202:203], s[32:33], 0, v[202:203]
	v_lshl_add_u64 v[202:203], v[202:203], 0, v[206:207]
	v_mov_b32_e32 v208, v200
	v_ashrrev_i32_e32 v209, 31, v200
	v_mov_b32_e32 v210, v201
	v_ashrrev_i32_e32 v211, 31, v201
	v_lshl_add_u64 v[208:209], v[208:209], 0, s[58:59]
	v_lshl_add_u64 v[210:211], v[210:211], 0, s[58:59]
	v_lshlrev_b64 v[208:209], 11, v[208:209]
	v_lshlrev_b64 v[210:211], 11, v[210:211]
	v_lshl_add_u64 v[208:209], s[8:9], 0, v[208:209]
	v_lshl_add_u64 v[210:211], s[8:9], 0, v[210:211]
	v_lshl_add_u64 v[208:209], v[208:209], 0, v[206:207]
	v_lshl_add_u64 v[210:211], v[210:211], 0, v[206:207]
	v_readfirstlane_b32 s61, v0
	s_nop 3
	s_lshl_b32 s61, s61, 4
	s_and_b32 s61, s61, 0xfffffc00
	s_mov_b32 m0, s61
	s_nop 0
	global_load_lds_dwordx4 v[208:209], off
	s_add_i32 m0, s61, 0x2000
	s_nop 0
	global_load_lds_dwordx4 v[210:211], off
	s_mov_b64 s[32:33], 0x4000000
	v_lshl_add_u64 v[230:231], v[202:203], 0, s[32:33]
	s_add_i32 m0, s61, 0x4000
	s_nop 0
	global_load_lds_dwordx4 v[230:231], off
	s_mov_b64 s[32:33], 0x4020000
	v_lshl_add_u64 v[212:213], v[202:203], 0, s[32:33]
	s_add_i32 m0, s61, 0x6000
	s_nop 0
	global_load_lds_dwordx4 v[212:213], off
	s_mov_b64 s[32:33], 0x4040000
	v_lshl_add_u64 v[214:215], v[202:203], 0, s[32:33]
	s_add_i32 m0, s61, 0x8000
	s_nop 0
	global_load_lds_dwordx4 v[214:215], off
	s_mov_b64 s[32:33], 0x4060000
	v_lshl_add_u64 v[216:217], v[202:203], 0, s[32:33]
	s_add_i32 m0, s61, 0xa000
	s_nop 0
	global_load_lds_dwordx4 v[216:217], off
	s_mov_b64 s[32:33], 0x80
	v_lshl_add_u64 v[218:219], v[208:209], 0, s[32:33]
	s_add_i32 m0, s61, 0xc000
	s_nop 0
	global_load_lds_dwordx4 v[218:219], off
	s_mov_b64 s[32:33], 0x80
	v_lshl_add_u64 v[220:221], v[210:211], 0, s[32:33]
	s_add_i32 m0, s61, 0xe000
	s_nop 0
	global_load_lds_dwordx4 v[220:221], off
	s_mov_b64 s[32:33], 0x4000080
	v_lshl_add_u64 v[222:223], v[202:203], 0, s[32:33]
	s_add_i32 m0, s61, 0x10000
	s_nop 0
	global_load_lds_dwordx4 v[222:223], off
	s_mov_b64 s[32:33], 0x4020080
	v_lshl_add_u64 v[224:225], v[202:203], 0, s[32:33]
	s_add_i32 m0, s61, 0x12000
	s_nop 0
	global_load_lds_dwordx4 v[224:225], off
	s_mov_b64 s[32:33], 0x4040080
	v_lshl_add_u64 v[226:227], v[202:203], 0, s[32:33]
	s_add_i32 m0, s61, 0x14000
	s_nop 0
	global_load_lds_dwordx4 v[226:227], off
	s_mov_b64 s[32:33], 0x4060080
	v_lshl_add_u64 v[228:229], v[202:203], 0, s[32:33]
	s_add_i32 m0, s61, 0x16000
	s_nop 0
	global_load_lds_dwordx4 v[228:229], off
	s_mov_b32 s99, 1
.Lpf15_p2_skip:
	global_store_dwordx2 v[72:73], v[58:59], off
	v_fma_f32 v58, -v1, v64, 1.0
	v_fmac_f32_e32 v64, v58, v64
	v_div_scale_f32 v58, vcc, v55, v63, v55
	v_mul_f32_e32 v59, v58, v64
	v_fma_f32 v60, -v1, v59, v58
	v_fmac_f32_e32 v59, v60, v64
	v_div_scale_f32 v60, s[58:59], v62, v62, v54
	v_rcp_f32_e32 v61, v60
	v_fma_f32 v1, -v1, v59, v58
	v_div_fmas_f32 v1, v1, v64, v59
	v_mul_f32_e32 v58, 0xbfb8aa3b, v56
	v_mul_f32_e32 v59, 0xbfb8aa3b, v57
	v_div_fixup_f32 v55, v1, v63, v55
	v_fma_f32 v1, -v60, v61, 1.0
	v_exp_f32_e32 v58, v58
	v_exp_f32_e32 v59, v59
	v_fmac_f32_e32 v61, v1, v61
	v_div_scale_f32 v1, vcc, v54, v62, v54
	v_mul_f32_e32 v63, v1, v61
	v_fma_f32 v64, -v60, v63, v1
	v_fmac_f32_e32 v63, v64, v61
	v_pk_add_f32 v[58:59], v[58:59], 1.0 op_sel_hi:[1,0]
	v_fma_f32 v1, -v60, v63, v1
	v_div_scale_f32 v60, s[58:59], v59, v59, v57
	v_rcp_f32_e32 v64, v60
	v_div_fmas_f32 v1, v1, v61, v63
	v_div_fixup_f32 v54, v1, v62, v54
	v_pk_mul_f32 v[50:51], v[50:51], v[54:55]
	v_fma_f32 v1, -v60, v64, 1.0
	v_fmac_f32_e32 v64, v1, v64
	v_div_scale_f32 v1, vcc, v57, v59, v57
	v_mul_f32_e32 v54, v1, v64
	v_fma_f32 v55, -v60, v54, v1
	v_fmac_f32_e32 v54, v55, v64
	v_fma_f32 v1, -v60, v54, v1
	v_div_scale_f32 v60, s[58:59], v58, v58, v56
	v_rcp_f32_e32 v61, v60
	v_div_fmas_f32 v1, v1, v64, v54
	v_div_fixup_f32 v55, v1, v59, v57
	v_cvt_pk_bf16_f32 v50, v50, v51
	v_fma_f32 v1, -v60, v61, 1.0
	v_fmac_f32_e32 v61, v1, v61
	v_div_scale_f32 v1, vcc, v56, v58, v56
	v_mul_f32_e32 v54, v1, v61
	v_fma_f32 v57, -v60, v54, v1
	v_fmac_f32_e32 v54, v57, v61
	v_fma_f32 v1, -v60, v54, v1
	v_div_fmas_f32 v1, v1, v61, v54
	v_div_fixup_f32 v54, v1, v58, v56
	v_pk_mul_f32 v[52:53], v[52:53], v[54:55]
	v_mul_f32_e32 v1, 0xbfb8aa3b, v42
	v_cvt_pk_bf16_f32 v51, v52, v53
	v_exp_f32_e32 v52, v1
	v_mul_f32_e32 v1, 0xbfb8aa3b, v43
	v_exp_f32_e32 v53, v1
	global_store_dwordx2 v[72:73], v[50:51], off offset:32
	v_or_b32_e32 v50, 16, v68
	v_ashrrev_i32_e32 v51, 31, v50
	v_pk_add_f32 v[52:53], v[52:53], 1.0 op_sel_hi:[1,0]
	v_lshlrev_b64 v[50:51], 11, v[50:51]
	v_div_scale_f32 v1, s[58:59], v53, v53, v43
	v_rcp_f32_e32 v54, v1
	v_lshl_add_u64 v[50:51], s[4:5], 0, v[50:51]
	v_lshl_add_u64 v[50:51], v[50:51], 0, s[2:3]
	v_lshl_add_u64 v[50:51], v[50:51], 0, v[66:67]
	v_fma_f32 v55, -v1, v54, 1.0
	v_fmac_f32_e32 v54, v55, v54
	v_div_scale_f32 v55, vcc, v43, v53, v43
	v_mul_f32_e32 v56, v55, v54
	v_fma_f32 v57, -v1, v56, v55
	v_fmac_f32_e32 v56, v57, v54
	v_div_scale_f32 v57, s[58:59], v52, v52, v42
	v_rcp_f32_e32 v58, v57
	v_fma_f32 v1, -v1, v56, v55
	v_div_fmas_f32 v1, v1, v54, v56
	v_mul_f32_e32 v54, 0xbfb8aa3b, v44
	v_mul_f32_e32 v55, 0xbfb8aa3b, v45
	v_exp_f32_e32 v54, v54
	v_exp_f32_e32 v55, v55
	v_div_fixup_f32 v43, v1, v53, v43
	v_fma_f32 v1, -v57, v58, 1.0
	v_fmac_f32_e32 v58, v1, v58
	v_div_scale_f32 v1, vcc, v42, v52, v42
	v_mul_f32_e32 v53, v1, v58
	v_fma_f32 v56, -v57, v53, v1
	v_pk_add_f32 v[54:55], v[54:55], 1.0 op_sel_hi:[1,0]
	v_fmac_f32_e32 v53, v56, v58
	v_div_scale_f32 v56, s[58:59], v55, v55, v45
	v_fma_f32 v1, -v57, v53, v1
	v_rcp_f32_e32 v57, v56
	v_div_fmas_f32 v1, v1, v58, v53
	v_div_fixup_f32 v42, v1, v52, v42
	v_pk_mul_f32 v[42:43], v[46:47], v[42:43]
	v_fma_f32 v1, -v56, v57, 1.0
	v_fmac_f32_e32 v57, v1, v57
	v_div_scale_f32 v1, vcc, v45, v55, v45
	v_mul_f32_e32 v46, v1, v57
	v_fma_f32 v47, -v56, v46, v1
	v_fmac_f32_e32 v46, v47, v57
	v_div_scale_f32 v47, s[58:59], v54, v54, v44
	v_rcp_f32_e32 v52, v47
	v_fma_f32 v1, -v56, v46, v1
	v_div_fmas_f32 v1, v1, v57, v46
	v_div_fixup_f32 v45, v1, v55, v45
	v_fma_f32 v1, -v47, v52, 1.0
	v_fmac_f32_e32 v52, v1, v52
	v_div_scale_f32 v1, vcc, v44, v54, v44
	v_mul_f32_e32 v53, v1, v52
	v_fma_f32 v46, -v47, v53, v1
	v_fmac_f32_e32 v53, v46, v52
	v_fma_f32 v1, -v47, v53, v1
	v_mul_f32_e32 v46, 0xbfb8aa3b, v38
	v_mul_f32_e32 v47, 0xbfb8aa3b, v39
	v_exp_f32_e32 v46, v46
	v_exp_f32_e32 v47, v47
	v_div_fmas_f32 v1, v1, v52, v53
	v_div_fixup_f32 v44, v1, v54, v44
	v_pk_mul_f32 v[44:45], v[48:49], v[44:45]
	v_pk_add_f32 v[46:47], v[46:47], 1.0 op_sel_hi:[1,0]
	v_lshl_add_u64 v[50:51], v[50:51], 0, v[70:71]
	v_div_scale_f32 v1, s[58:59], v47, v47, v39
	v_rcp_f32_e32 v48, v1
	v_cvt_pk_bf16_f32 v42, v42, v43
	v_cvt_pk_bf16_f32 v43, v44, v45
	global_store_dwordx2 v[50:51], v[42:43], off
	v_fma_f32 v42, -v1, v48, 1.0
	v_fmac_f32_e32 v48, v42, v48
	v_div_scale_f32 v42, vcc, v39, v47, v39
	v_mul_f32_e32 v43, v42, v48
	v_fma_f32 v44, -v1, v43, v42
	v_fmac_f32_e32 v43, v44, v48
	v_div_scale_f32 v44, s[58:59], v46, v46, v38
	v_rcp_f32_e32 v45, v44
	v_fma_f32 v1, -v1, v43, v42
	v_div_fmas_f32 v1, v1, v48, v43
	v_mul_f32_e32 v42, 0xbfb8aa3b, v40
	v_mul_f32_e32 v43, 0xbfb8aa3b, v41
	v_div_fixup_f32 v39, v1, v47, v39
	v_fma_f32 v1, -v44, v45, 1.0
	v_exp_f32_e32 v42, v42
	v_exp_f32_e32 v43, v43
	v_fmac_f32_e32 v45, v1, v45
	v_div_scale_f32 v1, vcc, v38, v46, v38
	v_mul_f32_e32 v47, v1, v45
	v_fma_f32 v48, -v44, v47, v1
	v_fmac_f32_e32 v47, v48, v45
	v_pk_add_f32 v[42:43], v[42:43], 1.0 op_sel_hi:[1,0]
	v_fma_f32 v1, -v44, v47, v1
	v_div_scale_f32 v44, s[58:59], v43, v43, v41
	v_rcp_f32_e32 v48, v44
	v_div_fmas_f32 v1, v1, v45, v47
	v_div_fixup_f32 v38, v1, v46, v38
	v_pk_mul_f32 v[34:35], v[34:35], v[38:39]
	v_fma_f32 v1, -v44, v48, 1.0
	v_fmac_f32_e32 v48, v1, v48
	v_div_scale_f32 v1, vcc, v41, v43, v41
	v_mul_f32_e32 v38, v1, v48
	v_fma_f32 v39, -v44, v38, v1
	v_fmac_f32_e32 v38, v39, v48
	v_fma_f32 v1, -v44, v38, v1
	v_div_scale_f32 v44, s[58:59], v42, v42, v40
	v_rcp_f32_e32 v45, v44
	v_div_fmas_f32 v1, v1, v48, v38
	v_div_fixup_f32 v39, v1, v43, v41
	v_cvt_pk_bf16_f32 v34, v34, v35
	v_fma_f32 v1, -v44, v45, 1.0
	v_fmac_f32_e32 v45, v1, v45
	v_div_scale_f32 v1, vcc, v40, v42, v40
	v_mul_f32_e32 v38, v1, v45
	v_fma_f32 v41, -v44, v38, v1
	v_fmac_f32_e32 v38, v41, v45
	v_fma_f32 v1, -v44, v38, v1
	v_div_fmas_f32 v1, v1, v45, v38
	v_div_fixup_f32 v38, v1, v42, v40
	v_pk_mul_f32 v[36:37], v[36:37], v[38:39]
	v_mul_f32_e32 v1, 0xbfb8aa3b, v26
	v_cvt_pk_bf16_f32 v35, v36, v37
	v_exp_f32_e32 v36, v1
	v_mul_f32_e32 v1, 0xbfb8aa3b, v27
	v_exp_f32_e32 v37, v1
	global_store_dwordx2 v[50:51], v[34:35], off offset:32
	v_or_b32_e32 v34, 32, v68
	v_ashrrev_i32_e32 v35, 31, v34
	v_pk_add_f32 v[36:37], v[36:37], 1.0 op_sel_hi:[1,0]
	v_lshlrev_b64 v[34:35], 11, v[34:35]
	v_div_scale_f32 v1, s[58:59], v37, v37, v27
	v_rcp_f32_e32 v38, v1
	v_lshl_add_u64 v[34:35], s[4:5], 0, v[34:35]
	v_lshl_add_u64 v[34:35], v[34:35], 0, s[2:3]
	v_lshl_add_u64 v[34:35], v[34:35], 0, v[66:67]
	v_fma_f32 v39, -v1, v38, 1.0
	v_fmac_f32_e32 v38, v39, v38
	v_div_scale_f32 v39, vcc, v27, v37, v27
	v_mul_f32_e32 v40, v39, v38
	v_fma_f32 v41, -v1, v40, v39
	v_fmac_f32_e32 v40, v41, v38
	v_div_scale_f32 v41, s[58:59], v36, v36, v26
	v_rcp_f32_e32 v42, v41
	v_fma_f32 v1, -v1, v40, v39
	v_div_fmas_f32 v1, v1, v38, v40
	v_mul_f32_e32 v38, 0xbfb8aa3b, v28
	v_mul_f32_e32 v39, 0xbfb8aa3b, v29
	v_exp_f32_e32 v38, v38
	v_exp_f32_e32 v39, v39
	v_div_fixup_f32 v27, v1, v37, v27
	v_fma_f32 v1, -v41, v42, 1.0
	v_fmac_f32_e32 v42, v1, v42
	v_div_scale_f32 v1, vcc, v26, v36, v26
	v_mul_f32_e32 v37, v1, v42
	v_fma_f32 v40, -v41, v37, v1
	v_pk_add_f32 v[38:39], v[38:39], 1.0 op_sel_hi:[1,0]
	v_fmac_f32_e32 v37, v40, v42
	v_div_scale_f32 v40, s[58:59], v39, v39, v29
	v_fma_f32 v1, -v41, v37, v1
	v_rcp_f32_e32 v41, v40
	v_div_fmas_f32 v1, v1, v42, v37
	v_div_fixup_f32 v26, v1, v36, v26
	v_pk_mul_f32 v[26:27], v[30:31], v[26:27]
	v_fma_f32 v1, -v40, v41, 1.0
	v_fmac_f32_e32 v41, v1, v41
	v_div_scale_f32 v1, vcc, v29, v39, v29
	v_mul_f32_e32 v30, v1, v41
	v_fma_f32 v31, -v40, v30, v1
	v_fmac_f32_e32 v30, v31, v41
	v_div_scale_f32 v31, s[58:59], v38, v38, v28
	v_rcp_f32_e32 v36, v31
	v_fma_f32 v1, -v40, v30, v1
	v_div_fmas_f32 v1, v1, v41, v30
	v_div_fixup_f32 v29, v1, v39, v29
	v_fma_f32 v1, -v31, v36, 1.0
	v_fmac_f32_e32 v36, v1, v36
	v_div_scale_f32 v1, vcc, v28, v38, v28
	v_mul_f32_e32 v37, v1, v36
	v_fma_f32 v30, -v31, v37, v1
	v_fmac_f32_e32 v37, v30, v36
	v_fma_f32 v1, -v31, v37, v1
	v_mul_f32_e32 v30, 0xbfb8aa3b, v22
	v_mul_f32_e32 v31, 0xbfb8aa3b, v23
	v_exp_f32_e32 v30, v30
	v_exp_f32_e32 v31, v31
	v_div_fmas_f32 v1, v1, v36, v37
	v_div_fixup_f32 v28, v1, v38, v28
	v_pk_mul_f32 v[28:29], v[32:33], v[28:29]
	v_pk_add_f32 v[30:31], v[30:31], 1.0 op_sel_hi:[1,0]
	v_lshl_add_u64 v[34:35], v[34:35], 0, v[70:71]
	v_div_scale_f32 v1, s[58:59], v31, v31, v23
	v_rcp_f32_e32 v32, v1
	v_cvt_pk_bf16_f32 v26, v26, v27
	v_cvt_pk_bf16_f32 v27, v28, v29
	global_store_dwordx2 v[34:35], v[26:27], off
	v_fma_f32 v26, -v1, v32, 1.0
	v_fmac_f32_e32 v32, v26, v32
	v_div_scale_f32 v26, vcc, v23, v31, v23
	v_mul_f32_e32 v27, v26, v32
	v_fma_f32 v28, -v1, v27, v26
	v_fmac_f32_e32 v27, v28, v32
	v_div_scale_f32 v28, s[58:59], v30, v30, v22
	v_rcp_f32_e32 v29, v28
	v_fma_f32 v1, -v1, v27, v26
	v_div_fmas_f32 v1, v1, v32, v27
	v_mul_f32_e32 v26, 0xbfb8aa3b, v24
	v_mul_f32_e32 v27, 0xbfb8aa3b, v25
	v_div_fixup_f32 v23, v1, v31, v23
	v_fma_f32 v1, -v28, v29, 1.0
	v_exp_f32_e32 v26, v26
	v_exp_f32_e32 v27, v27
	v_fmac_f32_e32 v29, v1, v29
	v_div_scale_f32 v1, vcc, v22, v30, v22
	v_mul_f32_e32 v31, v1, v29
	v_fma_f32 v32, -v28, v31, v1
	v_fmac_f32_e32 v31, v32, v29
	v_pk_add_f32 v[26:27], v[26:27], 1.0 op_sel_hi:[1,0]
	v_fma_f32 v1, -v28, v31, v1
	v_div_scale_f32 v28, s[58:59], v27, v27, v25
	v_rcp_f32_e32 v32, v28
	v_div_fmas_f32 v1, v1, v29, v31
	v_div_fixup_f32 v22, v1, v30, v22
	v_pk_mul_f32 v[18:19], v[18:19], v[22:23]
	v_fma_f32 v1, -v28, v32, 1.0
	v_fmac_f32_e32 v32, v1, v32
	v_div_scale_f32 v1, vcc, v25, v27, v25
	v_mul_f32_e32 v22, v1, v32
	v_fma_f32 v23, -v28, v22, v1
	v_fmac_f32_e32 v22, v23, v32
	v_fma_f32 v1, -v28, v22, v1
	v_div_scale_f32 v28, s[58:59], v26, v26, v24
	v_rcp_f32_e32 v29, v28
	v_div_fmas_f32 v1, v1, v32, v22
	v_div_fixup_f32 v23, v1, v27, v25
	v_cvt_pk_bf16_f32 v18, v18, v19
	v_fma_f32 v1, -v28, v29, 1.0
	v_fmac_f32_e32 v29, v1, v29
	v_div_scale_f32 v1, vcc, v24, v26, v24
	v_mul_f32_e32 v22, v1, v29
	v_fma_f32 v25, -v28, v22, v1
	v_fmac_f32_e32 v22, v25, v29
	v_fma_f32 v1, -v28, v22, v1
	v_div_fmas_f32 v1, v1, v29, v22
	v_div_fixup_f32 v22, v1, v26, v24
	v_pk_mul_f32 v[20:21], v[20:21], v[22:23]
	v_mul_f32_e32 v1, 0xbfb8aa3b, v10
	v_cvt_pk_bf16_f32 v19, v20, v21
	v_exp_f32_e32 v20, v1
	v_mul_f32_e32 v1, 0xbfb8aa3b, v11
	v_exp_f32_e32 v21, v1
	global_store_dwordx2 v[34:35], v[18:19], off offset:32
	v_or_b32_e32 v18, 48, v68
	v_ashrrev_i32_e32 v19, 31, v18
	v_lshlrev_b64 v[18:19], 11, v[18:19]
	v_pk_add_f32 v[20:21], v[20:21], 1.0 op_sel_hi:[1,0]
	v_lshl_add_u64 v[18:19], s[4:5], 0, v[18:19]
	v_div_scale_f32 v1, s[4:5], v21, v21, v11
	v_rcp_f32_e32 v22, v1
	v_lshl_add_u64 v[18:19], v[18:19], 0, s[2:3]
	v_lshl_add_u64 v[18:19], v[18:19], 0, v[66:67]
	v_lshl_add_u64 v[18:19], v[18:19], 0, v[70:71]
	v_fma_f32 v23, -v1, v22, 1.0
	v_fmac_f32_e32 v22, v23, v22
	v_div_scale_f32 v23, vcc, v11, v21, v11
	v_mul_f32_e32 v24, v23, v22
	v_fma_f32 v25, -v1, v24, v23
	v_fmac_f32_e32 v24, v25, v22
	v_div_scale_f32 v25, s[4:5], v20, v20, v10
	v_rcp_f32_e32 v26, v25
	v_fma_f32 v1, -v1, v24, v23
	v_div_fmas_f32 v1, v1, v22, v24
	v_mul_f32_e32 v22, 0xbfb8aa3b, v12
	v_mul_f32_e32 v23, 0xbfb8aa3b, v13
	v_exp_f32_e32 v22, v22
	v_exp_f32_e32 v23, v23
	v_div_fixup_f32 v11, v1, v21, v11
	v_fma_f32 v1, -v25, v26, 1.0
	v_fmac_f32_e32 v26, v1, v26
	v_div_scale_f32 v1, vcc, v10, v20, v10
	v_mul_f32_e32 v21, v1, v26
	v_fma_f32 v24, -v25, v21, v1
	v_pk_add_f32 v[22:23], v[22:23], 1.0 op_sel_hi:[1,0]
	v_fmac_f32_e32 v21, v24, v26
	v_div_scale_f32 v24, s[4:5], v23, v23, v13
	v_fma_f32 v1, -v25, v21, v1
	v_rcp_f32_e32 v25, v24
	v_div_fmas_f32 v1, v1, v26, v21
	v_div_fixup_f32 v10, v1, v20, v10
	v_pk_mul_f32 v[10:11], v[14:15], v[10:11]
	v_fma_f32 v1, -v24, v25, 1.0
	v_fmac_f32_e32 v25, v1, v25
	v_div_scale_f32 v1, vcc, v13, v23, v13
	v_mul_f32_e32 v14, v1, v25
	v_fma_f32 v15, -v24, v14, v1
	v_fmac_f32_e32 v14, v15, v25
	v_div_scale_f32 v15, s[4:5], v22, v22, v12
	v_rcp_f32_e32 v20, v15
	v_fma_f32 v1, -v24, v14, v1
	v_div_fmas_f32 v1, v1, v25, v14
	v_div_fixup_f32 v13, v1, v23, v13
	v_fma_f32 v1, -v15, v20, 1.0
	v_fmac_f32_e32 v20, v1, v20
	v_div_scale_f32 v1, vcc, v12, v22, v12
	v_mul_f32_e32 v21, v1, v20
	v_fma_f32 v14, -v15, v21, v1
	v_fmac_f32_e32 v21, v14, v20
	v_fma_f32 v1, -v15, v21, v1
	v_mul_f32_e32 v14, 0xbfb8aa3b, v6
	v_mul_f32_e32 v15, 0xbfb8aa3b, v7
	v_exp_f32_e32 v14, v14
	v_exp_f32_e32 v15, v15
	v_div_fmas_f32 v1, v1, v20, v21
	v_div_fixup_f32 v12, v1, v22, v12
	v_pk_mul_f32 v[12:13], v[16:17], v[12:13]
	v_pk_add_f32 v[14:15], v[14:15], 1.0 op_sel_hi:[1,0]
	v_cvt_pk_bf16_f32 v10, v10, v11
	v_div_scale_f32 v1, s[4:5], v15, v15, v7
	v_rcp_f32_e32 v16, v1
	v_cvt_pk_bf16_f32 v11, v12, v13
	global_store_dwordx2 v[18:19], v[10:11], off
	s_add_i32 s98, s98, s10
	v_fma_f32 v10, -v1, v16, 1.0
	v_fmac_f32_e32 v16, v10, v16
	v_div_scale_f32 v10, vcc, v7, v15, v7
	v_mul_f32_e32 v11, v10, v16
	v_fma_f32 v12, -v1, v11, v10
	v_fmac_f32_e32 v11, v12, v16
	v_div_scale_f32 v12, s[4:5], v14, v14, v6
	v_rcp_f32_e32 v13, v12
	v_fma_f32 v1, -v1, v11, v10
	v_div_fmas_f32 v1, v1, v16, v11
	v_mul_f32_e32 v10, 0xbfb8aa3b, v8
	v_mul_f32_e32 v11, 0xbfb8aa3b, v9
	v_div_fixup_f32 v7, v1, v15, v7
	v_fma_f32 v1, -v12, v13, 1.0
	v_exp_f32_e32 v10, v10
	v_exp_f32_e32 v11, v11
	v_fmac_f32_e32 v13, v1, v13
	v_div_scale_f32 v1, vcc, v6, v14, v6
	v_mul_f32_e32 v15, v1, v13
	v_fma_f32 v16, -v12, v15, v1
	v_fmac_f32_e32 v15, v16, v13
	v_pk_add_f32 v[10:11], v[10:11], 1.0 op_sel_hi:[1,0]
	v_fma_f32 v1, -v12, v15, v1
	v_div_scale_f32 v12, s[4:5], v11, v11, v9
	v_rcp_f32_e32 v16, v12
	v_div_fmas_f32 v1, v1, v13, v15
	v_div_fixup_f32 v6, v1, v14, v6
	v_pk_mul_f32 v[2:3], v[2:3], v[6:7]
	v_fma_f32 v1, -v12, v16, 1.0
	v_fmac_f32_e32 v16, v1, v16
	v_div_scale_f32 v1, vcc, v9, v11, v9
	v_mul_f32_e32 v6, v1, v16
	v_fma_f32 v7, -v12, v6, v1
	v_fmac_f32_e32 v6, v7, v16
	v_fma_f32 v1, -v12, v6, v1
	v_div_scale_f32 v12, s[4:5], v10, v10, v8
	v_rcp_f32_e32 v13, v12
	v_div_fmas_f32 v1, v1, v16, v6
	v_div_fixup_f32 v7, v1, v11, v9
	s_add_i32 s38, s38, s39
	v_fma_f32 v1, -v12, v13, 1.0
	v_fmac_f32_e32 v13, v1, v13
	v_div_scale_f32 v1, vcc, v8, v10, v8
	v_mul_f32_e32 v6, v1, v13
	v_fma_f32 v9, -v12, v6, v1
	v_fmac_f32_e32 v6, v9, v13
	v_fma_f32 v1, -v12, v6, v1
	v_div_fmas_f32 v1, v1, v13, v6
	v_div_fixup_f32 v6, v1, v10, v8
	v_pk_mul_f32 v[4:5], v[4:5], v[6:7]
	v_cvt_pk_bf16_f32 v2, v2, v3
	v_cvt_pk_bf16_f32 v3, v4, v5
	s_cmpk_lt_i32 s98, 0x800
	global_store_dwordx2 v[18:19], v[2:3], off offset:32
	s_cbranch_scc1 .LBB0_1435
	v_readlane_b32 s0, v197, 18
	v_readlane_b32 s47, v196, 5
	v_readlane_b32 s96, v196, 24
	s_mov_b32 s46, s10
	v_readlane_b32 s1, v197, 19
	v_readlane_b32 s97, v196, 25
